# adaLN GEMV loop hand-rewritten: 16 w_ada loads per batch double-buffered instead of vmcnt(0) after every load; same FMA order
# speedup vs baseline: 1.0444x; 1.0170x over previous
.LBB0_16:
	v_lshl_add_u64 v[16:17], v[6:7], 0, s[62:63]
	global_load_dword v40, v[16:17], off
	global_load_dword v41, v[16:17], off offset:2048
	v_add_u32_e32 v18, 0xfffd0000, v11
	s_movk_i32 s0, 0x1000
	v_add_u32_e32 v20, 0xfffe0000, v11
	v_and_b32_e32 v42, 0x7fe0, v18
	v_add_co_u32_e32 v18, vcc, s0, v16
	s_movk_i32 s0, 0x2000
	s_movk_i32 s2, 0x3000
	s_movk_i32 s4, 0x4000
	s_movk_i32 s6, 0x5000
	v_add_u32_e32 v19, s61, v66
	v_add_u32_e32 v21, s61, v64
	v_add_u32_e32 v23, 0xffff0000, v11
	v_add_u32_e32 v25, s61, v62
	v_and_b32_e32 v27, 0x7fe0, v11
	v_add_u32_e64 v29, 1, s61
	v_add_co_u32_e64 v22, s[0:1], s0, v16
	v_and_b32_e32 v43, 0x7fe0, v20
	v_add_co_u32_e64 v20, s[2:3], s2, v16
	v_add_co_u32_e64 v24, s[4:5], s4, v16
	v_add_co_u32_e64 v26, s[6:7], s6, v16
	v_add_co_u32_e64 v28, s[8:9], s65, v16
	s_movk_i32 s10, 0x7000
	v_xor_b32_e32 v44, v19, v1
	v_and_b32_e32 v45, 0x7fe0, v23
	v_xor_b32_e32 v46, v21, v1
	v_xor_b32_e32 v47, v25, v1
	v_lshlrev_b32_e32 v48, 2, v27
	v_add_co_u32_e64 v16, s[10:11], s10, v16
	v_xor_b32_e32 v49, v29, v1
	v_addc_co_u32_e32 v19, vcc, 0, v17, vcc
	v_addc_co_u32_e64 v23, vcc, 0, v17, s[0:1]
	v_addc_co_u32_e64 v21, vcc, 0, v17, s[2:3]
	v_addc_co_u32_e64 v25, vcc, 0, v17, s[4:5]
	v_addc_co_u32_e64 v27, vcc, 0, v17, s[6:7]
	v_addc_co_u32_e64 v29, vcc, 0, v17, s[8:9]
	v_addc_co_u32_e64 v17, vcc, 0, v17, s[10:11]
	global_load_dword v50, v[22:23], off offset:-4096
	s_nop 0
	global_load_dword v18, v[18:19], off offset:2048
	s_nop 0
	global_load_dword v19, v[22:23], off
	s_nop 0
	global_load_dword v22, v[22:23], off offset:2048
	s_nop 0
	global_load_dword v23, v[24:25], off offset:-4096
	s_nop 0
	global_load_dword v20, v[20:21], off offset:2048
	s_nop 0
	global_load_dword v21, v[24:25], off
	s_nop 0
	global_load_dword v24, v[24:25], off offset:2048
	s_nop 0
	global_load_dword v25, v[28:29], off offset:-4096
	s_nop 0
	global_load_dword v26, v[26:27], off offset:2048
	s_nop 0
	global_load_dword v27, v[28:29], off
	s_nop 0
	global_load_dword v28, v[28:29], off offset:2048
	s_nop 0
	global_load_dword v29, v[16:17], off
	s_nop 0
	global_load_dword v16, v[16:17], off offset:2048
	v_add_u32_e32 v13, s61, v68
	v_xor_b32_e32 v13, v13, v1
	v_lshlrev_b32_e32 v42, 2, v42
	v_lshlrev_b32_e32 v13, 2, v13
	v_lshlrev_b32_e32 v43, 2, v43
	v_lshlrev_b32_e32 v44, 2, v44
	v_lshlrev_b32_e32 v45, 2, v45
	v_lshlrev_b32_e32 v46, 2, v46
	v_add3_u32 v13, 0, v42, v13
	v_add3_u32 v17, 0, v43, v44
	v_add3_u32 v42, 0, v45, v46
	v_lshlrev_b32_e32 v47, 2, v47
	v_add3_u32 v43, 0, v48, v47
	v_xor_b32_e32 v15, s61, v1
	v_lshl_add_u32 v15, v15, 2, v58
	v_add_u32_e32 v30, s61, v67
	v_add_u32_e64 v31, 2, s61
	v_xor_b32_e32 v30, v30, v1
	v_lshl_add_u32 v49, v49, 2, v58
	v_xor_b32_e32 v31, v31, v1
	v_lshl_add_u32 v30, v30, 2, v59
	v_add_u32_e64 v32, 3, s61
	v_lshl_add_u32 v31, v31, 2, v58
	v_add_u32_e32 v33, s61, v65
	v_xor_b32_e32 v32, v32, v1
	v_add_u32_e64 v34, 4, s61
	v_xor_b32_e32 v33, v33, v1
	s_waitcnt vmcnt(15)
	v_mul_f32_e32 v44, 0xbfb8aa3b, v40
	s_waitcnt vmcnt(14)
	v_mul_f32_e32 v45, 0xbfb8aa3b, v41
	v_exp_f32_e32 v44, v44
	v_exp_f32_e32 v45, v45
	v_lshl_add_u32 v32, v32, 2, v58
	v_xor_b32_e32 v34, v34, v1
	v_add_f32_e32 v44, 1.0, v44
	v_add_f32_e32 v45, 1.0, v45
	v_div_scale_f32 v79, s[0:1], v44, v44, v40
	v_div_scale_f32 v81, s[0:1], v45, v45, v41
	v_rcp_f32_e32 v83, v79
	v_rcp_f32_e32 v84, v81
	v_div_scale_f32 v80, vcc, v40, v44, v40
	v_fma_f32 v127, -v79, v83, 1.0
	v_fma_f32 v128, -v81, v84, 1.0
	v_div_scale_f32 v82, s[30:31], v41, v45, v41
	v_fmac_f32_e32 v83, v127, v83
	v_fmac_f32_e32 v84, v128, v84
	v_mul_f32_e32 v127, v80, v83
	v_mul_f32_e32 v128, v82, v84
	v_fma_f32 v143, -v79, v127, v80
	v_fma_f32 v144, -v81, v128, v82
	v_fmac_f32_e32 v127, v143, v83
	v_fmac_f32_e32 v128, v144, v84
	v_fma_f32 v79, -v79, v127, v80
	v_fma_f32 v80, -v81, v128, v82
	v_div_fmas_f32 v79, v79, v83, v127
	s_mov_b64 vcc, s[30:31]
	v_div_fixup_f32 v40, v79, v44, v40
	v_div_fmas_f32 v44, v80, v84, v128
	ds_write_b32 v15, v40
	v_div_fixup_f32 v15, v44, v45, v41
	ds_write_b32 v13, v15
	v_lshl_add_u32 v33, v33, 2, v59
	v_add_u32_e64 v35, 5, s61
	s_waitcnt vmcnt(13)
	v_mul_f32_e32 v46, 0xbfb8aa3b, v50
	s_waitcnt vmcnt(12)
	v_mul_f32_e32 v47, 0xbfb8aa3b, v18
	v_exp_f32_e32 v46, v46
	s_waitcnt vmcnt(11)
	v_mul_f32_e32 v48, 0xbfb8aa3b, v19
	v_exp_f32_e32 v47, v47
	s_waitcnt vmcnt(10)
	v_mul_f32_e32 v51, 0xbfb8aa3b, v22
	v_exp_f32_e32 v48, v48
	s_waitcnt vmcnt(9)
	v_mul_f32_e32 v52, 0xbfb8aa3b, v23
	v_exp_f32_e32 v51, v51
	s_waitcnt vmcnt(8)
	v_mul_f32_e32 v53, 0xbfb8aa3b, v20
	v_exp_f32_e32 v52, v52
	v_add_f32_e32 v46, 1.0, v46
	s_waitcnt vmcnt(7)
	v_mul_f32_e32 v71, 0xbfb8aa3b, v21
	v_exp_f32_e32 v53, v53
	v_add_f32_e32 v47, 1.0, v47
	v_div_scale_f32 v85, s[0:1], v46, v46, v50
	s_waitcnt vmcnt(6)
	v_mul_f32_e32 v72, 0xbfb8aa3b, v24
	v_exp_f32_e32 v71, v71
	v_add_f32_e32 v48, 1.0, v48
	v_div_scale_f32 v87, s[0:1], v47, v47, v18
	v_rcp_f32_e32 v113, v85
	s_waitcnt vmcnt(5)
	v_mul_f32_e32 v73, 0xbfb8aa3b, v25
	v_exp_f32_e32 v72, v72
	v_add_f32_e32 v51, 1.0, v51
	v_div_scale_f32 v89, s[0:1], v48, v48, v19
	v_rcp_f32_e32 v114, v87
	s_waitcnt vmcnt(4)
	v_mul_f32_e32 v74, 0xbfb8aa3b, v26
	v_exp_f32_e32 v73, v73
	v_add_f32_e32 v52, 1.0, v52
	v_div_scale_f32 v91, s[0:1], v51, v51, v22
	v_rcp_f32_e32 v115, v89
	s_waitcnt vmcnt(3)
	v_mul_f32_e32 v75, 0xbfb8aa3b, v27
	v_exp_f32_e32 v74, v74
	v_add_f32_e32 v53, 1.0, v53
	v_div_scale_f32 v93, s[0:1], v52, v52, v23
	v_rcp_f32_e32 v116, v91
	s_waitcnt vmcnt(2)
	v_mul_f32_e32 v76, 0xbfb8aa3b, v28
	v_exp_f32_e32 v75, v75
	v_add_f32_e32 v71, 1.0, v71
	v_div_scale_f32 v95, s[0:1], v53, v53, v20
	v_rcp_f32_e32 v117, v93
	v_fma_f32 v129, -v85, v113, 1.0
	s_waitcnt vmcnt(1)
	v_mul_f32_e32 v77, 0xbfb8aa3b, v29
	v_exp_f32_e32 v76, v76
	v_add_f32_e32 v72, 1.0, v72
	v_div_scale_f32 v86, s[28:29], v50, v46, v50
	v_div_scale_f32 v97, s[0:1], v71, v71, v21
	v_rcp_f32_e32 v118, v95
	v_fma_f32 v130, -v87, v114, 1.0
	v_fmac_f32_e32 v113, v129, v113
	s_waitcnt vmcnt(0)
	v_mul_f32_e32 v78, 0xbfb8aa3b, v16
	v_exp_f32_e32 v77, v77
	v_add_f32_e32 v73, 1.0, v73
	v_div_scale_f32 v88, s[26:27], v18, v47, v18
	v_div_scale_f32 v99, s[0:1], v72, v72, v24
	v_rcp_f32_e32 v119, v97
	v_fma_f32 v131, -v89, v115, 1.0
	v_fmac_f32_e32 v114, v130, v114
	v_mul_f32_e32 v129, v86, v113
	v_exp_f32_e32 v78, v78
	v_add_f32_e32 v74, 1.0, v74
	v_div_scale_f32 v90, s[24:25], v19, v48, v19
	v_div_scale_f32 v101, s[0:1], v73, v73, v25
	v_rcp_f32_e32 v120, v99
	v_fma_f32 v132, -v91, v116, 1.0
	v_fmac_f32_e32 v115, v131, v115
	v_mul_f32_e32 v130, v88, v114
	v_fma_f32 v81, -v85, v129, v86
	v_add_f32_e32 v75, 1.0, v75
	v_div_scale_f32 v92, s[22:23], v22, v51, v22
	v_div_scale_f32 v103, s[0:1], v74, v74, v26
	v_rcp_f32_e32 v121, v101
	v_fma_f32 v133, -v93, v117, 1.0
	v_fmac_f32_e32 v116, v132, v116
	v_mul_f32_e32 v131, v90, v115
	v_fma_f32 v82, -v87, v130, v88
	v_fmac_f32_e32 v129, v81, v113
	v_add_f32_e32 v76, 1.0, v76
	v_div_scale_f32 v94, s[20:21], v23, v52, v23
	v_div_scale_f32 v105, s[0:1], v75, v75, v27
	v_rcp_f32_e32 v122, v103
	v_fma_f32 v134, -v95, v118, 1.0
	v_fmac_f32_e32 v117, v133, v117
	v_mul_f32_e32 v132, v92, v116
	v_fma_f32 v143, -v89, v131, v90
	v_fmac_f32_e32 v130, v82, v114
	v_fma_f32 v79, -v85, v129, v86
	s_mov_b64 vcc, s[28:29]
	v_add_f32_e32 v77, 1.0, v77
	v_div_scale_f32 v96, s[18:19], v20, v53, v20
	v_div_scale_f32 v107, s[0:1], v76, v76, v28
	v_rcp_f32_e32 v123, v105
	v_fma_f32 v135, -v97, v119, 1.0
	v_fmac_f32_e32 v118, v134, v118
	v_mul_f32_e32 v133, v94, v117
	v_fma_f32 v144, -v91, v132, v92
	v_fmac_f32_e32 v131, v143, v115
	v_fma_f32 v80, -v87, v130, v88
	v_div_fmas_f32 v40, v79, v113, v129
	s_mov_b64 vcc, s[26:27]
	v_add_f32_e32 v78, 1.0, v78
	v_div_scale_f32 v98, s[16:17], v21, v71, v21
	v_div_scale_f32 v109, s[0:1], v77, v77, v29
	v_rcp_f32_e32 v124, v107
	v_fma_f32 v136, -v99, v120, 1.0
	v_fmac_f32_e32 v119, v135, v119
	v_mul_f32_e32 v134, v96, v118
	v_fma_f32 v145, -v93, v133, v94
	v_fmac_f32_e32 v132, v144, v116
	v_fma_f32 v81, -v89, v131, v90
	v_div_fixup_f32 v13, v40, v46, v50
	v_div_fmas_f32 v15, v80, v114, v130
	s_mov_b64 vcc, s[24:25]
	v_div_scale_f32 v100, s[14:15], v24, v72, v24
	v_div_scale_f32 v110, s[0:1], v78, v78, v16
	v_rcp_f32_e32 v125, v109
	v_fma_f32 v137, -v101, v121, 1.0
	v_fmac_f32_e32 v120, v136, v120
	v_mul_f32_e32 v135, v98, v119
	v_fma_f32 v146, -v95, v134, v96
	v_fmac_f32_e32 v133, v145, v117
	v_fma_f32 v82, -v91, v132, v92
	ds_write_b32 v49, v13
	v_div_fixup_f32 v13, v15, v47, v18
	v_div_fmas_f32 v15, v81, v115, v131
	s_mov_b64 vcc, s[22:23]
	v_div_scale_f32 v102, s[12:13], v25, v73, v25
	v_rcp_f32_e32 v126, v110
	v_fma_f32 v138, -v103, v122, 1.0
	v_fmac_f32_e32 v121, v137, v121
	v_mul_f32_e32 v136, v100, v120
	v_fma_f32 v147, -v97, v135, v98
	v_fmac_f32_e32 v134, v146, v118
	v_fma_f32 v83, -v93, v133, v94
	ds_write_b32 v30, v13
	v_div_fixup_f32 v13, v15, v48, v19
	v_div_fmas_f32 v15, v82, v116, v132
	s_mov_b64 vcc, s[20:21]
	v_div_scale_f32 v104, s[10:11], v26, v74, v26
	v_fma_f32 v139, -v105, v123, 1.0
	v_fmac_f32_e32 v122, v138, v122
	v_mul_f32_e32 v137, v102, v121
	v_fma_f32 v148, -v99, v136, v100
	v_fmac_f32_e32 v135, v147, v119
	v_fma_f32 v84, -v95, v134, v96
	ds_write_b32 v31, v13
	v_div_fixup_f32 v13, v15, v51, v22
	v_div_fmas_f32 v15, v83, v117, v133
	s_mov_b64 vcc, s[18:19]
	v_div_scale_f32 v106, s[8:9], v27, v75, v27
	v_fma_f32 v140, -v107, v124, 1.0
	v_fmac_f32_e32 v123, v139, v123
	v_mul_f32_e32 v138, v104, v122
	v_fma_f32 v149, -v101, v137, v102
	v_fmac_f32_e32 v136, v148, v120
	v_fma_f32 v85, -v97, v135, v98
	ds_write_b32 v17, v13
	v_div_fixup_f32 v13, v15, v52, v23
	v_div_fmas_f32 v15, v84, v118, v134
	s_mov_b64 vcc, s[16:17]
	v_div_scale_f32 v108, s[6:7], v28, v76, v28
	v_fma_f32 v141, -v109, v125, 1.0
	v_fmac_f32_e32 v124, v140, v124
	v_mul_f32_e32 v139, v106, v123
	v_fma_f32 v150, -v103, v138, v104
	v_fmac_f32_e32 v137, v149, v121
	v_fma_f32 v86, -v99, v136, v100
	ds_write_b32 v32, v13
	v_div_fixup_f32 v13, v15, v53, v20
	v_div_fmas_f32 v15, v85, v119, v135
	s_mov_b64 vcc, s[14:15]
	v_lshl_add_u32 v34, v34, 2, v58
	v_div_scale_f32 v111, s[4:5], v29, v77, v29
	v_fma_f32 v142, -v110, v126, 1.0
	v_fmac_f32_e32 v125, v141, v125
	v_mul_f32_e32 v140, v108, v124
	v_fma_f32 v151, -v105, v139, v106
	v_fmac_f32_e32 v138, v150, v122
	v_fma_f32 v87, -v101, v137, v102
	ds_write_b32 v33, v13
	v_div_fixup_f32 v13, v15, v71, v21
	v_div_fmas_f32 v15, v86, v120, v136
	s_mov_b64 vcc, s[12:13]
	v_add_u32_e32 v36, s61, v63
	v_xor_b32_e32 v35, v35, v1
	v_div_scale_f32 v112, s[2:3], v16, v78, v16
	v_fmac_f32_e32 v126, v142, v126
	v_mul_f32_e32 v141, v111, v125
	v_fma_f32 v152, -v107, v140, v108
	v_fmac_f32_e32 v139, v151, v123
	v_fma_f32 v88, -v103, v138, v104
	ds_write_b32 v34, v13
	v_div_fixup_f32 v13, v15, v72, v24
	v_div_fmas_f32 v15, v87, v121, v137
	s_mov_b64 vcc, s[10:11]
	v_add_u32_e64 v37, 6, s61
	v_xor_b32_e32 v36, v36, v1
	v_lshl_add_u32 v35, v35, 2, v58
	v_mul_f32_e32 v142, v112, v126
	v_fma_f32 v153, -v109, v141, v111
	v_fmac_f32_e32 v140, v152, v124
	v_fma_f32 v89, -v105, v139, v106
	ds_write_b32 v42, v13
	v_div_fixup_f32 v13, v15, v73, v25
	v_div_fmas_f32 v15, v88, v122, v138
	s_mov_b64 vcc, s[8:9]
	v_xor_b32_e32 v37, v37, v1
	v_lshl_add_u32 v36, v36, 2, v59
	v_fma_f32 v154, -v110, v142, v112
	v_fmac_f32_e32 v141, v153, v125
	v_fma_f32 v90, -v107, v140, v108
	ds_write_b32 v35, v13
	v_div_fixup_f32 v13, v15, v74, v26
	v_div_fmas_f32 v15, v89, v123, v139
	s_mov_b64 vcc, s[6:7]
	v_add_u32_e64 v38, 7, s61
	v_add_u32_e32 v39, s61, v60
	s_add_i32 s61, s61, 8
	v_lshl_add_u32 v37, v37, 2, v58
	v_fmac_f32_e32 v142, v154, v126
	v_fma_f32 v91, -v109, v141, v111
	ds_write_b32 v36, v13
	v_div_fixup_f32 v13, v15, v75, v27
	v_div_fmas_f32 v15, v90, v124, v140
	s_mov_b64 vcc, s[4:5]
	v_xor_b32_e32 v38, v38, v1
	s_add_u32 s62, s62, 0x8000
	v_fma_f32 v92, -v110, v142, v112
	ds_write_b32 v37, v13
	v_div_fixup_f32 v13, v15, v76, v28
	v_div_fmas_f32 v15, v91, v125, v141
	s_mov_b64 vcc, s[2:3]
	v_xor_b32_e32 v39, v39, v1
	v_lshl_add_u32 v38, v38, 2, v58
	s_addc_u32 s63, s63, 0
	ds_write_b32 v43, v13
	v_div_fixup_f32 v13, v15, v77, v29
	v_div_fmas_f32 v15, v92, v126, v142
	v_add_u32_e32 v11, 0x40000, v11
	v_lshl_add_u32 v39, v39, 2, v59
	s_cmp_eq_u32 s62, 0x20000
	ds_write_b32 v38, v13
	v_div_fixup_f32 v13, v15, v78, v16
	ds_write_b32 v39, v13
	s_cbranch_scc0 .LBB0_16
	s_ashr_i32 s61, s60, 31
	v_mov_b32_e32 v20, 0
	v_lshl_add_u64 v[16:17], s[60:61], 2, v[8:9]
	s_mov_b64 s[0:1], 0
	v_mov_b32_e32 v11, v69
	v_mov_b32_e32 v21, v20
	v_mov_b32_e32 v22, v20
	v_mov_b32_e32 v23, v20
	v_mov_b32_e32 v24, v20
	v_mov_b32_e32 v25, v20
	v_mov_b32_e32 v26, v20
	v_mov_b32_e32 v27, v20
	v_mov_b32_e32 v30, v20
	v_mov_b32_e32 v31, v20
	v_mov_b32_e32 v44, v20
	v_mov_b32_e32 v45, v20
	v_mov_b32_e32 v46, v20
	v_mov_b32_e32 v47, v20
	v_mov_b32_e32 v48, v20
	v_mov_b32_e32 v49, v20
	v_mov_b32_e32 v50, v20
	v_mov_b32_e32 v51, v20
	v_mov_b32_e32 v28, v20
	v_mov_b32_e32 v29, v20
	v_mov_b32_e32 v32, v20
	v_mov_b32_e32 v33, v20
	v_mov_b32_e32 v34, v20
	v_mov_b32_e32 v35, v20
	v_mov_b32_e32 v36, v20
	v_mov_b32_e32 v37, v20
	v_mov_b32_e32 v38, v20
	v_mov_b32_e32 v39, v20
	v_mov_b32_e32 v40, v20
	v_mov_b32_e32 v41, v20
	v_mov_b32_e32 v42, v20
	v_mov_b32_e32 v43, v20
	s_waitcnt lgkmcnt(0)
	s_barrier
	s_mov_b32 s2, 0x6000
	s_mov_b32 s3, 0
	s_mov_b32 s4, 0
	v_lshl_add_u64 v[18:19], v[16:17], 0, s[0:1]
	s_add_u32 s0, s0, 0x60000
	s_addc_u32 s1, s1, 0
	global_load_dword v96, v[18:19], off
	v_lshl_add_u64 v[18:19], v[18:19], 0, s[2:3]
	global_load_dword v97, v[18:19], off
	v_lshl_add_u64 v[18:19], v[18:19], 0, s[2:3]
	global_load_dword v98, v[18:19], off
	v_lshl_add_u64 v[18:19], v[18:19], 0, s[2:3]
	global_load_dword v99, v[18:19], off
	v_lshl_add_u64 v[18:19], v[18:19], 0, s[2:3]
	global_load_dword v100, v[18:19], off
	v_lshl_add_u64 v[18:19], v[18:19], 0, s[2:3]
	global_load_dword v101, v[18:19], off
	v_lshl_add_u64 v[18:19], v[18:19], 0, s[2:3]
	global_load_dword v102, v[18:19], off
	v_lshl_add_u64 v[18:19], v[18:19], 0, s[2:3]
	global_load_dword v103, v[18:19], off
	v_lshl_add_u64 v[18:19], v[18:19], 0, s[2:3]
	global_load_dword v104, v[18:19], off
	v_lshl_add_u64 v[18:19], v[18:19], 0, s[2:3]
	global_load_dword v105, v[18:19], off
	v_lshl_add_u64 v[18:19], v[18:19], 0, s[2:3]
	global_load_dword v106, v[18:19], off
	v_lshl_add_u64 v[18:19], v[18:19], 0, s[2:3]
	global_load_dword v107, v[18:19], off
	v_lshl_add_u64 v[18:19], v[18:19], 0, s[2:3]
	global_load_dword v108, v[18:19], off
	v_lshl_add_u64 v[18:19], v[18:19], 0, s[2:3]
	global_load_dword v109, v[18:19], off
	v_lshl_add_u64 v[18:19], v[18:19], 0, s[2:3]
	global_load_dword v110, v[18:19], off
	v_lshl_add_u64 v[18:19], v[18:19], 0, s[2:3]
	global_load_dword v111, v[18:19], off
.Lada_loop:
	v_lshl_add_u64 v[18:19], v[16:17], 0, s[0:1]
	s_add_u32 s0, s0, 0x60000
	s_addc_u32 s1, s1, 0
	global_load_dword v112, v[18:19], off
	v_lshl_add_u64 v[18:19], v[18:19], 0, s[2:3]
	global_load_dword v113, v[18:19], off
	v_lshl_add_u64 v[18:19], v[18:19], 0, s[2:3]
	global_load_dword v114, v[18:19], off
	v_lshl_add_u64 v[18:19], v[18:19], 0, s[2:3]
	global_load_dword v115, v[18:19], off
	v_lshl_add_u64 v[18:19], v[18:19], 0, s[2:3]
	global_load_dword v116, v[18:19], off
	v_lshl_add_u64 v[18:19], v[18:19], 0, s[2:3]
	global_load_dword v117, v[18:19], off
	v_lshl_add_u64 v[18:19], v[18:19], 0, s[2:3]
	global_load_dword v118, v[18:19], off
	v_lshl_add_u64 v[18:19], v[18:19], 0, s[2:3]
	global_load_dword v119, v[18:19], off
	v_lshl_add_u64 v[18:19], v[18:19], 0, s[2:3]
	global_load_dword v120, v[18:19], off
	v_lshl_add_u64 v[18:19], v[18:19], 0, s[2:3]
	global_load_dword v121, v[18:19], off
	v_lshl_add_u64 v[18:19], v[18:19], 0, s[2:3]
	global_load_dword v122, v[18:19], off
	v_lshl_add_u64 v[18:19], v[18:19], 0, s[2:3]
	global_load_dword v123, v[18:19], off
	v_lshl_add_u64 v[18:19], v[18:19], 0, s[2:3]
	global_load_dword v124, v[18:19], off
	v_lshl_add_u64 v[18:19], v[18:19], 0, s[2:3]
	global_load_dword v125, v[18:19], off
	v_lshl_add_u64 v[18:19], v[18:19], 0, s[2:3]
	global_load_dword v126, v[18:19], off
	v_lshl_add_u64 v[18:19], v[18:19], 0, s[2:3]
	global_load_dword v127, v[18:19], off
	ds_read_b128 v[128:131], v11
	ds_read_b128 v[132:135], v11 offset:16
	ds_read_b128 v[136:139], v11 offset:32
	ds_read_b128 v[140:143], v11 offset:48
	ds_read_b128 v[144:147], v11 offset:64
	ds_read_b128 v[148:151], v11 offset:80
	ds_read_b128 v[152:155], v11 offset:96
	ds_read_b128 v[156:159], v11 offset:112
	s_waitcnt vmcnt(16)
	s_waitcnt lgkmcnt(0)
	ds_read_b128 v[160:163], v11 offset:144
	ds_read_b128 v[164:167], v11 offset:128
	ds_read_b128 v[168:171], v11 offset:176
	ds_read_b128 v[172:175], v11 offset:160
	ds_read_b128 v[176:179], v11 offset:208
	ds_read_b128 v[180:183], v11 offset:192
	ds_read_b128 v[184:187], v11 offset:240
	ds_read_b128 v[188:191], v11 offset:224
	v_pk_fma_f32 v[22:23], v[96:97], v[128:129], v[22:23] op_sel_hi:[0,1,1]
	v_pk_fma_f32 v[24:25], v[96:97], v[130:131], v[24:25] op_sel_hi:[0,1,1]
	v_pk_fma_f32 v[26:27], v[96:97], v[132:133], v[26:27] op_sel_hi:[0,1,1]
	v_pk_fma_f32 v[30:31], v[96:97], v[134:135], v[30:31] op_sel_hi:[0,1,1]
	v_pk_fma_f32 v[44:45], v[96:97], v[136:137], v[44:45] op_sel_hi:[0,1,1]
	v_pk_fma_f32 v[46:47], v[96:97], v[138:139], v[46:47] op_sel_hi:[0,1,1]
	v_pk_fma_f32 v[48:49], v[96:97], v[140:141], v[48:49] op_sel_hi:[0,1,1]
	v_pk_fma_f32 v[50:51], v[96:97], v[142:143], v[50:51] op_sel_hi:[0,1,1]
	v_pk_fma_f32 v[28:29], v[96:97], v[144:145], v[28:29] op_sel_hi:[0,1,1]
	v_pk_fma_f32 v[32:33], v[96:97], v[146:147], v[32:33] op_sel_hi:[0,1,1]
	v_pk_fma_f32 v[34:35], v[96:97], v[148:149], v[34:35] op_sel_hi:[0,1,1]
	v_pk_fma_f32 v[36:37], v[96:97], v[150:151], v[36:37] op_sel_hi:[0,1,1]
	v_pk_fma_f32 v[38:39], v[96:97], v[152:153], v[38:39] op_sel_hi:[0,1,1]
	v_pk_fma_f32 v[40:41], v[96:97], v[154:155], v[40:41] op_sel_hi:[0,1,1]
	v_pk_fma_f32 v[42:43], v[96:97], v[156:157], v[42:43] op_sel_hi:[0,1,1]
	v_pk_fma_f32 v[20:21], v[96:97], v[158:159], v[20:21] op_sel_hi:[0,1,1]
	s_waitcnt lgkmcnt(0)
	ds_read_b128 v[128:131], v11 offset:288
	ds_read_b128 v[132:135], v11 offset:304
	ds_read_b128 v[136:139], v11 offset:256
	ds_read_b128 v[140:143], v11 offset:272
	ds_read_b128 v[144:147], v11 offset:352
	ds_read_b128 v[148:151], v11 offset:368
	ds_read_b128 v[152:155], v11 offset:320
	ds_read_b128 v[156:159], v11 offset:336
	v_pk_fma_f32 v[22:23], v[96:97], v[160:161], v[22:23] op_sel:[1,0,0] op_sel_hi:[1,1,1]
	v_pk_fma_f32 v[24:25], v[96:97], v[162:163], v[24:25] op_sel:[1,0,0] op_sel_hi:[1,1,1]
	v_pk_fma_f32 v[26:27], v[96:97], v[164:165], v[26:27] op_sel:[1,0,0] op_sel_hi:[1,1,1]
	v_pk_fma_f32 v[30:31], v[96:97], v[166:167], v[30:31] op_sel:[1,0,0] op_sel_hi:[1,1,1]
	v_pk_fma_f32 v[44:45], v[96:97], v[168:169], v[44:45] op_sel:[1,0,0] op_sel_hi:[1,1,1]
	v_pk_fma_f32 v[46:47], v[96:97], v[170:171], v[46:47] op_sel:[1,0,0] op_sel_hi:[1,1,1]
	v_pk_fma_f32 v[48:49], v[96:97], v[172:173], v[48:49] op_sel:[1,0,0] op_sel_hi:[1,1,1]
	v_pk_fma_f32 v[50:51], v[96:97], v[174:175], v[50:51] op_sel:[1,0,0] op_sel_hi:[1,1,1]
	v_pk_fma_f32 v[28:29], v[96:97], v[176:177], v[28:29] op_sel:[1,0,0] op_sel_hi:[1,1,1]
	v_pk_fma_f32 v[32:33], v[96:97], v[178:179], v[32:33] op_sel:[1,0,0] op_sel_hi:[1,1,1]
	v_pk_fma_f32 v[34:35], v[96:97], v[180:181], v[34:35] op_sel:[1,0,0] op_sel_hi:[1,1,1]
	v_pk_fma_f32 v[36:37], v[96:97], v[182:183], v[36:37] op_sel:[1,0,0] op_sel_hi:[1,1,1]
	v_pk_fma_f32 v[38:39], v[96:97], v[184:185], v[38:39] op_sel:[1,0,0] op_sel_hi:[1,1,1]
	v_pk_fma_f32 v[40:41], v[96:97], v[186:187], v[40:41] op_sel:[1,0,0] op_sel_hi:[1,1,1]
	v_pk_fma_f32 v[42:43], v[96:97], v[188:189], v[42:43] op_sel:[1,0,0] op_sel_hi:[1,1,1]
	v_pk_fma_f32 v[20:21], v[96:97], v[190:191], v[20:21] op_sel:[1,0,0] op_sel_hi:[1,1,1]
	s_waitcnt lgkmcnt(0)
	ds_read_b128 v[160:163], v11 offset:432
	ds_read_b128 v[164:167], v11 offset:416
	ds_read_b128 v[168:171], v11 offset:400
	ds_read_b128 v[172:175], v11 offset:384
	ds_read_b128 v[176:179], v11 offset:496
	ds_read_b128 v[180:183], v11 offset:480
	ds_read_b128 v[184:187], v11 offset:464
	ds_read_b128 v[188:191], v11 offset:448
	v_pk_fma_f32 v[22:23], v[98:99], v[128:129], v[22:23] op_sel_hi:[0,1,1]
	v_pk_fma_f32 v[24:25], v[98:99], v[130:131], v[24:25] op_sel_hi:[0,1,1]
	v_pk_fma_f32 v[26:27], v[98:99], v[132:133], v[26:27] op_sel_hi:[0,1,1]
	v_pk_fma_f32 v[30:31], v[98:99], v[134:135], v[30:31] op_sel_hi:[0,1,1]
	v_pk_fma_f32 v[44:45], v[98:99], v[136:137], v[44:45] op_sel_hi:[0,1,1]
	v_pk_fma_f32 v[46:47], v[98:99], v[138:139], v[46:47] op_sel_hi:[0,1,1]
	v_pk_fma_f32 v[48:49], v[98:99], v[140:141], v[48:49] op_sel_hi:[0,1,1]
	v_pk_fma_f32 v[50:51], v[98:99], v[142:143], v[50:51] op_sel_hi:[0,1,1]
	v_pk_fma_f32 v[28:29], v[98:99], v[144:145], v[28:29] op_sel_hi:[0,1,1]
	v_pk_fma_f32 v[32:33], v[98:99], v[146:147], v[32:33] op_sel_hi:[0,1,1]
	v_pk_fma_f32 v[34:35], v[98:99], v[148:149], v[34:35] op_sel_hi:[0,1,1]
	v_pk_fma_f32 v[36:37], v[98:99], v[150:151], v[36:37] op_sel_hi:[0,1,1]
	v_pk_fma_f32 v[38:39], v[98:99], v[152:153], v[38:39] op_sel_hi:[0,1,1]
	v_pk_fma_f32 v[40:41], v[98:99], v[154:155], v[40:41] op_sel_hi:[0,1,1]
	v_pk_fma_f32 v[42:43], v[98:99], v[156:157], v[42:43] op_sel_hi:[0,1,1]
	v_pk_fma_f32 v[20:21], v[98:99], v[158:159], v[20:21] op_sel_hi:[0,1,1]
	s_waitcnt lgkmcnt(0)
	ds_read_b128 v[128:131], v11 offset:576
	ds_read_b128 v[132:135], v11 offset:592
	ds_read_b128 v[136:139], v11 offset:608
	ds_read_b128 v[140:143], v11 offset:624
	ds_read_b128 v[144:147], v11 offset:512
	ds_read_b128 v[148:151], v11 offset:528
	ds_read_b128 v[152:155], v11 offset:544
	ds_read_b128 v[156:159], v11 offset:560
	v_pk_fma_f32 v[22:23], v[98:99], v[160:161], v[22:23] op_sel:[1,0,0] op_sel_hi:[1,1,1]
	v_pk_fma_f32 v[24:25], v[98:99], v[162:163], v[24:25] op_sel:[1,0,0] op_sel_hi:[1,1,1]
	v_pk_fma_f32 v[26:27], v[98:99], v[164:165], v[26:27] op_sel:[1,0,0] op_sel_hi:[1,1,1]
	v_pk_fma_f32 v[30:31], v[98:99], v[166:167], v[30:31] op_sel:[1,0,0] op_sel_hi:[1,1,1]
	v_pk_fma_f32 v[44:45], v[98:99], v[168:169], v[44:45] op_sel:[1,0,0] op_sel_hi:[1,1,1]
	v_pk_fma_f32 v[46:47], v[98:99], v[170:171], v[46:47] op_sel:[1,0,0] op_sel_hi:[1,1,1]
	v_pk_fma_f32 v[48:49], v[98:99], v[172:173], v[48:49] op_sel:[1,0,0] op_sel_hi:[1,1,1]
	v_pk_fma_f32 v[50:51], v[98:99], v[174:175], v[50:51] op_sel:[1,0,0] op_sel_hi:[1,1,1]
	v_pk_fma_f32 v[28:29], v[98:99], v[176:177], v[28:29] op_sel:[1,0,0] op_sel_hi:[1,1,1]
	v_pk_fma_f32 v[32:33], v[98:99], v[178:179], v[32:33] op_sel:[1,0,0] op_sel_hi:[1,1,1]
	v_pk_fma_f32 v[34:35], v[98:99], v[180:181], v[34:35] op_sel:[1,0,0] op_sel_hi:[1,1,1]
	v_pk_fma_f32 v[36:37], v[98:99], v[182:183], v[36:37] op_sel:[1,0,0] op_sel_hi:[1,1,1]
	v_pk_fma_f32 v[38:39], v[98:99], v[184:185], v[38:39] op_sel:[1,0,0] op_sel_hi:[1,1,1]
	v_pk_fma_f32 v[40:41], v[98:99], v[186:187], v[40:41] op_sel:[1,0,0] op_sel_hi:[1,1,1]
	v_pk_fma_f32 v[42:43], v[98:99], v[188:189], v[42:43] op_sel:[1,0,0] op_sel_hi:[1,1,1]
	v_pk_fma_f32 v[20:21], v[98:99], v[190:191], v[20:21] op_sel:[1,0,0] op_sel_hi:[1,1,1]
	s_waitcnt lgkmcnt(0)
	ds_read_b128 v[160:163], v11 offset:720
	ds_read_b128 v[164:167], v11 offset:704
	ds_read_b128 v[168:171], v11 offset:752
	ds_read_b128 v[172:175], v11 offset:736
	ds_read_b128 v[176:179], v11 offset:656
	ds_read_b128 v[180:183], v11 offset:640
	ds_read_b128 v[184:187], v11 offset:688
	ds_read_b128 v[188:191], v11 offset:672
	v_pk_fma_f32 v[22:23], v[100:101], v[128:129], v[22:23] op_sel_hi:[0,1,1]
	v_pk_fma_f32 v[24:25], v[100:101], v[130:131], v[24:25] op_sel_hi:[0,1,1]
	v_pk_fma_f32 v[26:27], v[100:101], v[132:133], v[26:27] op_sel_hi:[0,1,1]
	v_pk_fma_f32 v[30:31], v[100:101], v[134:135], v[30:31] op_sel_hi:[0,1,1]
	v_pk_fma_f32 v[44:45], v[100:101], v[136:137], v[44:45] op_sel_hi:[0,1,1]
	v_pk_fma_f32 v[46:47], v[100:101], v[138:139], v[46:47] op_sel_hi:[0,1,1]
	v_pk_fma_f32 v[48:49], v[100:101], v[140:141], v[48:49] op_sel_hi:[0,1,1]
	v_pk_fma_f32 v[50:51], v[100:101], v[142:143], v[50:51] op_sel_hi:[0,1,1]
	v_pk_fma_f32 v[28:29], v[100:101], v[144:145], v[28:29] op_sel_hi:[0,1,1]
	v_pk_fma_f32 v[32:33], v[100:101], v[146:147], v[32:33] op_sel_hi:[0,1,1]
	v_pk_fma_f32 v[34:35], v[100:101], v[148:149], v[34:35] op_sel_hi:[0,1,1]
	v_pk_fma_f32 v[36:37], v[100:101], v[150:151], v[36:37] op_sel_hi:[0,1,1]
	v_pk_fma_f32 v[38:39], v[100:101], v[152:153], v[38:39] op_sel_hi:[0,1,1]
	v_pk_fma_f32 v[40:41], v[100:101], v[154:155], v[40:41] op_sel_hi:[0,1,1]
	v_pk_fma_f32 v[42:43], v[100:101], v[156:157], v[42:43] op_sel_hi:[0,1,1]
	v_pk_fma_f32 v[20:21], v[100:101], v[158:159], v[20:21] op_sel_hi:[0,1,1]
	s_waitcnt lgkmcnt(0)
	ds_read_b128 v[128:131], v11 offset:864
	ds_read_b128 v[132:135], v11 offset:880
	ds_read_b128 v[136:139], v11 offset:832
	ds_read_b128 v[140:143], v11 offset:848
	ds_read_b128 v[144:147], v11 offset:800
	ds_read_b128 v[148:151], v11 offset:816
	ds_read_b128 v[152:155], v11 offset:768
	ds_read_b128 v[156:159], v11 offset:784
	v_pk_fma_f32 v[22:23], v[100:101], v[160:161], v[22:23] op_sel:[1,0,0] op_sel_hi:[1,1,1]
	v_pk_fma_f32 v[24:25], v[100:101], v[162:163], v[24:25] op_sel:[1,0,0] op_sel_hi:[1,1,1]
	v_pk_fma_f32 v[26:27], v[100:101], v[164:165], v[26:27] op_sel:[1,0,0] op_sel_hi:[1,1,1]
	v_pk_fma_f32 v[30:31], v[100:101], v[166:167], v[30:31] op_sel:[1,0,0] op_sel_hi:[1,1,1]
	v_pk_fma_f32 v[44:45], v[100:101], v[168:169], v[44:45] op_sel:[1,0,0] op_sel_hi:[1,1,1]
	v_pk_fma_f32 v[46:47], v[100:101], v[170:171], v[46:47] op_sel:[1,0,0] op_sel_hi:[1,1,1]
	v_pk_fma_f32 v[48:49], v[100:101], v[172:173], v[48:49] op_sel:[1,0,0] op_sel_hi:[1,1,1]
	v_pk_fma_f32 v[50:51], v[100:101], v[174:175], v[50:51] op_sel:[1,0,0] op_sel_hi:[1,1,1]
	v_pk_fma_f32 v[28:29], v[100:101], v[176:177], v[28:29] op_sel:[1,0,0] op_sel_hi:[1,1,1]
	v_pk_fma_f32 v[32:33], v[100:101], v[178:179], v[32:33] op_sel:[1,0,0] op_sel_hi:[1,1,1]
	v_pk_fma_f32 v[34:35], v[100:101], v[180:181], v[34:35] op_sel:[1,0,0] op_sel_hi:[1,1,1]
	v_pk_fma_f32 v[36:37], v[100:101], v[182:183], v[36:37] op_sel:[1,0,0] op_sel_hi:[1,1,1]
	v_pk_fma_f32 v[38:39], v[100:101], v[184:185], v[38:39] op_sel:[1,0,0] op_sel_hi:[1,1,1]
	v_pk_fma_f32 v[40:41], v[100:101], v[186:187], v[40:41] op_sel:[1,0,0] op_sel_hi:[1,1,1]
	v_pk_fma_f32 v[42:43], v[100:101], v[188:189], v[42:43] op_sel:[1,0,0] op_sel_hi:[1,1,1]
	v_pk_fma_f32 v[20:21], v[100:101], v[190:191], v[20:21] op_sel:[1,0,0] op_sel_hi:[1,1,1]
	s_waitcnt lgkmcnt(0)
	ds_read_b128 v[160:163], v11 offset:1008
	ds_read_b128 v[164:167], v11 offset:992
	ds_read_b128 v[168:171], v11 offset:976
	ds_read_b128 v[172:175], v11 offset:960
	ds_read_b128 v[176:179], v11 offset:944
	ds_read_b128 v[180:183], v11 offset:928
	ds_read_b128 v[184:187], v11 offset:912
	ds_read_b128 v[188:191], v11 offset:896
	v_pk_fma_f32 v[22:23], v[102:103], v[128:129], v[22:23] op_sel_hi:[0,1,1]
	v_pk_fma_f32 v[24:25], v[102:103], v[130:131], v[24:25] op_sel_hi:[0,1,1]
	v_pk_fma_f32 v[26:27], v[102:103], v[132:133], v[26:27] op_sel_hi:[0,1,1]
	v_pk_fma_f32 v[30:31], v[102:103], v[134:135], v[30:31] op_sel_hi:[0,1,1]
	v_pk_fma_f32 v[44:45], v[102:103], v[136:137], v[44:45] op_sel_hi:[0,1,1]
	v_pk_fma_f32 v[46:47], v[102:103], v[138:139], v[46:47] op_sel_hi:[0,1,1]
	v_pk_fma_f32 v[48:49], v[102:103], v[140:141], v[48:49] op_sel_hi:[0,1,1]
	v_pk_fma_f32 v[50:51], v[102:103], v[142:143], v[50:51] op_sel_hi:[0,1,1]
	v_pk_fma_f32 v[28:29], v[102:103], v[144:145], v[28:29] op_sel_hi:[0,1,1]
	v_pk_fma_f32 v[32:33], v[102:103], v[146:147], v[32:33] op_sel_hi:[0,1,1]
	v_pk_fma_f32 v[34:35], v[102:103], v[148:149], v[34:35] op_sel_hi:[0,1,1]
	v_pk_fma_f32 v[36:37], v[102:103], v[150:151], v[36:37] op_sel_hi:[0,1,1]
	v_pk_fma_f32 v[38:39], v[102:103], v[152:153], v[38:39] op_sel_hi:[0,1,1]
	v_pk_fma_f32 v[40:41], v[102:103], v[154:155], v[40:41] op_sel_hi:[0,1,1]
	v_pk_fma_f32 v[42:43], v[102:103], v[156:157], v[42:43] op_sel_hi:[0,1,1]
	v_pk_fma_f32 v[20:21], v[102:103], v[158:159], v[20:21] op_sel_hi:[0,1,1]
	s_waitcnt lgkmcnt(0)
	ds_read_b128 v[128:131], v11 offset:1024
	ds_read_b128 v[132:135], v11 offset:1040
	ds_read_b128 v[136:139], v11 offset:1056
	ds_read_b128 v[140:143], v11 offset:1072
	ds_read_b128 v[144:147], v11 offset:1088
	ds_read_b128 v[148:151], v11 offset:1104
	ds_read_b128 v[152:155], v11 offset:1120
	ds_read_b128 v[156:159], v11 offset:1136
	v_pk_fma_f32 v[22:23], v[102:103], v[160:161], v[22:23] op_sel:[1,0,0] op_sel_hi:[1,1,1]
	v_pk_fma_f32 v[24:25], v[102:103], v[162:163], v[24:25] op_sel:[1,0,0] op_sel_hi:[1,1,1]
	v_pk_fma_f32 v[26:27], v[102:103], v[164:165], v[26:27] op_sel:[1,0,0] op_sel_hi:[1,1,1]
	v_pk_fma_f32 v[30:31], v[102:103], v[166:167], v[30:31] op_sel:[1,0,0] op_sel_hi:[1,1,1]
	v_pk_fma_f32 v[44:45], v[102:103], v[168:169], v[44:45] op_sel:[1,0,0] op_sel_hi:[1,1,1]
	v_pk_fma_f32 v[46:47], v[102:103], v[170:171], v[46:47] op_sel:[1,0,0] op_sel_hi:[1,1,1]
	v_pk_fma_f32 v[48:49], v[102:103], v[172:173], v[48:49] op_sel:[1,0,0] op_sel_hi:[1,1,1]
	v_pk_fma_f32 v[50:51], v[102:103], v[174:175], v[50:51] op_sel:[1,0,0] op_sel_hi:[1,1,1]
	v_pk_fma_f32 v[28:29], v[102:103], v[176:177], v[28:29] op_sel:[1,0,0] op_sel_hi:[1,1,1]
	v_pk_fma_f32 v[32:33], v[102:103], v[178:179], v[32:33] op_sel:[1,0,0] op_sel_hi:[1,1,1]
	v_pk_fma_f32 v[34:35], v[102:103], v[180:181], v[34:35] op_sel:[1,0,0] op_sel_hi:[1,1,1]
	v_pk_fma_f32 v[36:37], v[102:103], v[182:183], v[36:37] op_sel:[1,0,0] op_sel_hi:[1,1,1]
	v_pk_fma_f32 v[38:39], v[102:103], v[184:185], v[38:39] op_sel:[1,0,0] op_sel_hi:[1,1,1]
	v_pk_fma_f32 v[40:41], v[102:103], v[186:187], v[40:41] op_sel:[1,0,0] op_sel_hi:[1,1,1]
	v_pk_fma_f32 v[42:43], v[102:103], v[188:189], v[42:43] op_sel:[1,0,0] op_sel_hi:[1,1,1]
	v_pk_fma_f32 v[20:21], v[102:103], v[190:191], v[20:21] op_sel:[1,0,0] op_sel_hi:[1,1,1]
	s_waitcnt lgkmcnt(0)
	ds_read_b128 v[160:163], v11 offset:1168
	ds_read_b128 v[164:167], v11 offset:1152
	ds_read_b128 v[168:171], v11 offset:1200
	ds_read_b128 v[172:175], v11 offset:1184
	ds_read_b128 v[176:179], v11 offset:1232
	ds_read_b128 v[180:183], v11 offset:1216
	ds_read_b128 v[184:187], v11 offset:1264
	ds_read_b128 v[188:191], v11 offset:1248
	v_pk_fma_f32 v[22:23], v[104:105], v[128:129], v[22:23] op_sel_hi:[0,1,1]
	v_pk_fma_f32 v[24:25], v[104:105], v[130:131], v[24:25] op_sel_hi:[0,1,1]
	v_pk_fma_f32 v[26:27], v[104:105], v[132:133], v[26:27] op_sel_hi:[0,1,1]
	v_pk_fma_f32 v[30:31], v[104:105], v[134:135], v[30:31] op_sel_hi:[0,1,1]
	v_pk_fma_f32 v[44:45], v[104:105], v[136:137], v[44:45] op_sel_hi:[0,1,1]
	v_pk_fma_f32 v[46:47], v[104:105], v[138:139], v[46:47] op_sel_hi:[0,1,1]
	v_pk_fma_f32 v[48:49], v[104:105], v[140:141], v[48:49] op_sel_hi:[0,1,1]
	v_pk_fma_f32 v[50:51], v[104:105], v[142:143], v[50:51] op_sel_hi:[0,1,1]
	v_pk_fma_f32 v[28:29], v[104:105], v[144:145], v[28:29] op_sel_hi:[0,1,1]
	v_pk_fma_f32 v[32:33], v[104:105], v[146:147], v[32:33] op_sel_hi:[0,1,1]
	v_pk_fma_f32 v[34:35], v[104:105], v[148:149], v[34:35] op_sel_hi:[0,1,1]
	v_pk_fma_f32 v[36:37], v[104:105], v[150:151], v[36:37] op_sel_hi:[0,1,1]
	v_pk_fma_f32 v[38:39], v[104:105], v[152:153], v[38:39] op_sel_hi:[0,1,1]
	v_pk_fma_f32 v[40:41], v[104:105], v[154:155], v[40:41] op_sel_hi:[0,1,1]
	v_pk_fma_f32 v[42:43], v[104:105], v[156:157], v[42:43] op_sel_hi:[0,1,1]
	v_pk_fma_f32 v[20:21], v[104:105], v[158:159], v[20:21] op_sel_hi:[0,1,1]
	s_waitcnt lgkmcnt(0)
	ds_read_b128 v[128:131], v11 offset:1312
	ds_read_b128 v[132:135], v11 offset:1328
	ds_read_b128 v[136:139], v11 offset:1280
	ds_read_b128 v[140:143], v11 offset:1296
	ds_read_b128 v[144:147], v11 offset:1376
	ds_read_b128 v[148:151], v11 offset:1392
	ds_read_b128 v[152:155], v11 offset:1344
	ds_read_b128 v[156:159], v11 offset:1360
	v_pk_fma_f32 v[22:23], v[104:105], v[160:161], v[22:23] op_sel:[1,0,0] op_sel_hi:[1,1,1]
	v_pk_fma_f32 v[24:25], v[104:105], v[162:163], v[24:25] op_sel:[1,0,0] op_sel_hi:[1,1,1]
	v_pk_fma_f32 v[26:27], v[104:105], v[164:165], v[26:27] op_sel:[1,0,0] op_sel_hi:[1,1,1]
	v_pk_fma_f32 v[30:31], v[104:105], v[166:167], v[30:31] op_sel:[1,0,0] op_sel_hi:[1,1,1]
	v_pk_fma_f32 v[44:45], v[104:105], v[168:169], v[44:45] op_sel:[1,0,0] op_sel_hi:[1,1,1]
	v_pk_fma_f32 v[46:47], v[104:105], v[170:171], v[46:47] op_sel:[1,0,0] op_sel_hi:[1,1,1]
	v_pk_fma_f32 v[48:49], v[104:105], v[172:173], v[48:49] op_sel:[1,0,0] op_sel_hi:[1,1,1]
	v_pk_fma_f32 v[50:51], v[104:105], v[174:175], v[50:51] op_sel:[1,0,0] op_sel_hi:[1,1,1]
	v_pk_fma_f32 v[28:29], v[104:105], v[176:177], v[28:29] op_sel:[1,0,0] op_sel_hi:[1,1,1]
	v_pk_fma_f32 v[32:33], v[104:105], v[178:179], v[32:33] op_sel:[1,0,0] op_sel_hi:[1,1,1]
	v_pk_fma_f32 v[34:35], v[104:105], v[180:181], v[34:35] op_sel:[1,0,0] op_sel_hi:[1,1,1]
	v_pk_fma_f32 v[36:37], v[104:105], v[182:183], v[36:37] op_sel:[1,0,0] op_sel_hi:[1,1,1]
	v_pk_fma_f32 v[38:39], v[104:105], v[184:185], v[38:39] op_sel:[1,0,0] op_sel_hi:[1,1,1]
	v_pk_fma_f32 v[40:41], v[104:105], v[186:187], v[40:41] op_sel:[1,0,0] op_sel_hi:[1,1,1]
	v_pk_fma_f32 v[42:43], v[104:105], v[188:189], v[42:43] op_sel:[1,0,0] op_sel_hi:[1,1,1]
	v_pk_fma_f32 v[20:21], v[104:105], v[190:191], v[20:21] op_sel:[1,0,0] op_sel_hi:[1,1,1]
	s_waitcnt lgkmcnt(0)
	ds_read_b128 v[160:163], v11 offset:1456
	ds_read_b128 v[164:167], v11 offset:1440
	ds_read_b128 v[168:171], v11 offset:1424
	ds_read_b128 v[172:175], v11 offset:1408
	ds_read_b128 v[176:179], v11 offset:1520
	ds_read_b128 v[180:183], v11 offset:1504
	ds_read_b128 v[184:187], v11 offset:1488
	ds_read_b128 v[188:191], v11 offset:1472
	v_pk_fma_f32 v[22:23], v[106:107], v[128:129], v[22:23] op_sel_hi:[0,1,1]
	v_pk_fma_f32 v[24:25], v[106:107], v[130:131], v[24:25] op_sel_hi:[0,1,1]
	v_pk_fma_f32 v[26:27], v[106:107], v[132:133], v[26:27] op_sel_hi:[0,1,1]
	v_pk_fma_f32 v[30:31], v[106:107], v[134:135], v[30:31] op_sel_hi:[0,1,1]
	v_pk_fma_f32 v[44:45], v[106:107], v[136:137], v[44:45] op_sel_hi:[0,1,1]
	v_pk_fma_f32 v[46:47], v[106:107], v[138:139], v[46:47] op_sel_hi:[0,1,1]
	v_pk_fma_f32 v[48:49], v[106:107], v[140:141], v[48:49] op_sel_hi:[0,1,1]
	v_pk_fma_f32 v[50:51], v[106:107], v[142:143], v[50:51] op_sel_hi:[0,1,1]
	v_pk_fma_f32 v[28:29], v[106:107], v[144:145], v[28:29] op_sel_hi:[0,1,1]
	v_pk_fma_f32 v[32:33], v[106:107], v[146:147], v[32:33] op_sel_hi:[0,1,1]
	v_pk_fma_f32 v[34:35], v[106:107], v[148:149], v[34:35] op_sel_hi:[0,1,1]
	v_pk_fma_f32 v[36:37], v[106:107], v[150:151], v[36:37] op_sel_hi:[0,1,1]
	v_pk_fma_f32 v[38:39], v[106:107], v[152:153], v[38:39] op_sel_hi:[0,1,1]
	v_pk_fma_f32 v[40:41], v[106:107], v[154:155], v[40:41] op_sel_hi:[0,1,1]
	v_pk_fma_f32 v[42:43], v[106:107], v[156:157], v[42:43] op_sel_hi:[0,1,1]
	v_pk_fma_f32 v[20:21], v[106:107], v[158:159], v[20:21] op_sel_hi:[0,1,1]
	s_waitcnt lgkmcnt(0)
	ds_read_b128 v[128:131], v11 offset:1600
	ds_read_b128 v[132:135], v11 offset:1616
	ds_read_b128 v[136:139], v11 offset:1632
	ds_read_b128 v[140:143], v11 offset:1648
	ds_read_b128 v[144:147], v11 offset:1536
	ds_read_b128 v[148:151], v11 offset:1552
	ds_read_b128 v[152:155], v11 offset:1568
	ds_read_b128 v[156:159], v11 offset:1584
	v_pk_fma_f32 v[22:23], v[106:107], v[160:161], v[22:23] op_sel:[1,0,0] op_sel_hi:[1,1,1]
	v_pk_fma_f32 v[24:25], v[106:107], v[162:163], v[24:25] op_sel:[1,0,0] op_sel_hi:[1,1,1]
	v_pk_fma_f32 v[26:27], v[106:107], v[164:165], v[26:27] op_sel:[1,0,0] op_sel_hi:[1,1,1]
	v_pk_fma_f32 v[30:31], v[106:107], v[166:167], v[30:31] op_sel:[1,0,0] op_sel_hi:[1,1,1]
	v_pk_fma_f32 v[44:45], v[106:107], v[168:169], v[44:45] op_sel:[1,0,0] op_sel_hi:[1,1,1]
	v_pk_fma_f32 v[46:47], v[106:107], v[170:171], v[46:47] op_sel:[1,0,0] op_sel_hi:[1,1,1]
	v_pk_fma_f32 v[48:49], v[106:107], v[172:173], v[48:49] op_sel:[1,0,0] op_sel_hi:[1,1,1]
	v_pk_fma_f32 v[50:51], v[106:107], v[174:175], v[50:51] op_sel:[1,0,0] op_sel_hi:[1,1,1]
	v_pk_fma_f32 v[28:29], v[106:107], v[176:177], v[28:29] op_sel:[1,0,0] op_sel_hi:[1,1,1]
	v_pk_fma_f32 v[32:33], v[106:107], v[178:179], v[32:33] op_sel:[1,0,0] op_sel_hi:[1,1,1]
	v_pk_fma_f32 v[34:35], v[106:107], v[180:181], v[34:35] op_sel:[1,0,0] op_sel_hi:[1,1,1]
	v_pk_fma_f32 v[36:37], v[106:107], v[182:183], v[36:37] op_sel:[1,0,0] op_sel_hi:[1,1,1]
	v_pk_fma_f32 v[38:39], v[106:107], v[184:185], v[38:39] op_sel:[1,0,0] op_sel_hi:[1,1,1]
	v_pk_fma_f32 v[40:41], v[106:107], v[186:187], v[40:41] op_sel:[1,0,0] op_sel_hi:[1,1,1]
	v_pk_fma_f32 v[42:43], v[106:107], v[188:189], v[42:43] op_sel:[1,0,0] op_sel_hi:[1,1,1]
	v_pk_fma_f32 v[20:21], v[106:107], v[190:191], v[20:21] op_sel:[1,0,0] op_sel_hi:[1,1,1]
	s_waitcnt lgkmcnt(0)
	ds_read_b128 v[160:163], v11 offset:1744
	ds_read_b128 v[164:167], v11 offset:1728
	ds_read_b128 v[168:171], v11 offset:1776
	ds_read_b128 v[172:175], v11 offset:1760
	ds_read_b128 v[176:179], v11 offset:1680
	ds_read_b128 v[180:183], v11 offset:1664
	ds_read_b128 v[184:187], v11 offset:1712
	ds_read_b128 v[188:191], v11 offset:1696
	v_pk_fma_f32 v[22:23], v[108:109], v[128:129], v[22:23] op_sel_hi:[0,1,1]
	v_pk_fma_f32 v[24:25], v[108:109], v[130:131], v[24:25] op_sel_hi:[0,1,1]
	v_pk_fma_f32 v[26:27], v[108:109], v[132:133], v[26:27] op_sel_hi:[0,1,1]
	v_pk_fma_f32 v[30:31], v[108:109], v[134:135], v[30:31] op_sel_hi:[0,1,1]
	v_pk_fma_f32 v[44:45], v[108:109], v[136:137], v[44:45] op_sel_hi:[0,1,1]
	v_pk_fma_f32 v[46:47], v[108:109], v[138:139], v[46:47] op_sel_hi:[0,1,1]
	v_pk_fma_f32 v[48:49], v[108:109], v[140:141], v[48:49] op_sel_hi:[0,1,1]
	v_pk_fma_f32 v[50:51], v[108:109], v[142:143], v[50:51] op_sel_hi:[0,1,1]
	v_pk_fma_f32 v[28:29], v[108:109], v[144:145], v[28:29] op_sel_hi:[0,1,1]
	v_pk_fma_f32 v[32:33], v[108:109], v[146:147], v[32:33] op_sel_hi:[0,1,1]
	v_pk_fma_f32 v[34:35], v[108:109], v[148:149], v[34:35] op_sel_hi:[0,1,1]
	v_pk_fma_f32 v[36:37], v[108:109], v[150:151], v[36:37] op_sel_hi:[0,1,1]
	v_pk_fma_f32 v[38:39], v[108:109], v[152:153], v[38:39] op_sel_hi:[0,1,1]
	v_pk_fma_f32 v[40:41], v[108:109], v[154:155], v[40:41] op_sel_hi:[0,1,1]
	v_pk_fma_f32 v[42:43], v[108:109], v[156:157], v[42:43] op_sel_hi:[0,1,1]
	v_pk_fma_f32 v[20:21], v[108:109], v[158:159], v[20:21] op_sel_hi:[0,1,1]
	s_waitcnt lgkmcnt(0)
	ds_read_b128 v[128:131], v11 offset:1888
	ds_read_b128 v[132:135], v11 offset:1904
	ds_read_b128 v[136:139], v11 offset:1856
	ds_read_b128 v[140:143], v11 offset:1872
	ds_read_b128 v[144:147], v11 offset:1824
	ds_read_b128 v[148:151], v11 offset:1840
	ds_read_b128 v[152:155], v11 offset:1792
	ds_read_b128 v[156:159], v11 offset:1808
	v_pk_fma_f32 v[22:23], v[108:109], v[160:161], v[22:23] op_sel:[1,0,0] op_sel_hi:[1,1,1]
	v_pk_fma_f32 v[24:25], v[108:109], v[162:163], v[24:25] op_sel:[1,0,0] op_sel_hi:[1,1,1]
	v_pk_fma_f32 v[26:27], v[108:109], v[164:165], v[26:27] op_sel:[1,0,0] op_sel_hi:[1,1,1]
	v_pk_fma_f32 v[30:31], v[108:109], v[166:167], v[30:31] op_sel:[1,0,0] op_sel_hi:[1,1,1]
	v_pk_fma_f32 v[44:45], v[108:109], v[168:169], v[44:45] op_sel:[1,0,0] op_sel_hi:[1,1,1]
	v_pk_fma_f32 v[46:47], v[108:109], v[170:171], v[46:47] op_sel:[1,0,0] op_sel_hi:[1,1,1]
	v_pk_fma_f32 v[48:49], v[108:109], v[172:173], v[48:49] op_sel:[1,0,0] op_sel_hi:[1,1,1]
	v_pk_fma_f32 v[50:51], v[108:109], v[174:175], v[50:51] op_sel:[1,0,0] op_sel_hi:[1,1,1]
	v_pk_fma_f32 v[28:29], v[108:109], v[176:177], v[28:29] op_sel:[1,0,0] op_sel_hi:[1,1,1]
	v_pk_fma_f32 v[32:33], v[108:109], v[178:179], v[32:33] op_sel:[1,0,0] op_sel_hi:[1,1,1]
	v_pk_fma_f32 v[34:35], v[108:109], v[180:181], v[34:35] op_sel:[1,0,0] op_sel_hi:[1,1,1]
	v_pk_fma_f32 v[36:37], v[108:109], v[182:183], v[36:37] op_sel:[1,0,0] op_sel_hi:[1,1,1]
	v_pk_fma_f32 v[38:39], v[108:109], v[184:185], v[38:39] op_sel:[1,0,0] op_sel_hi:[1,1,1]
	v_pk_fma_f32 v[40:41], v[108:109], v[186:187], v[40:41] op_sel:[1,0,0] op_sel_hi:[1,1,1]
	v_pk_fma_f32 v[42:43], v[108:109], v[188:189], v[42:43] op_sel:[1,0,0] op_sel_hi:[1,1,1]
	v_pk_fma_f32 v[20:21], v[108:109], v[190:191], v[20:21] op_sel:[1,0,0] op_sel_hi:[1,1,1]
	s_waitcnt lgkmcnt(0)
	ds_read_b128 v[160:163], v11 offset:2032
	ds_read_b128 v[164:167], v11 offset:2016
	ds_read_b128 v[168:171], v11 offset:2000
	ds_read_b128 v[172:175], v11 offset:1984
	ds_read_b128 v[176:179], v11 offset:1968
	ds_read_b128 v[180:183], v11 offset:1952
	ds_read_b128 v[184:187], v11 offset:1936
	ds_read_b128 v[188:191], v11 offset:1920
	v_pk_fma_f32 v[22:23], v[110:111], v[128:129], v[22:23] op_sel_hi:[0,1,1]
	v_pk_fma_f32 v[24:25], v[110:111], v[130:131], v[24:25] op_sel_hi:[0,1,1]
	v_pk_fma_f32 v[26:27], v[110:111], v[132:133], v[26:27] op_sel_hi:[0,1,1]
	v_pk_fma_f32 v[30:31], v[110:111], v[134:135], v[30:31] op_sel_hi:[0,1,1]
	v_pk_fma_f32 v[44:45], v[110:111], v[136:137], v[44:45] op_sel_hi:[0,1,1]
	v_pk_fma_f32 v[46:47], v[110:111], v[138:139], v[46:47] op_sel_hi:[0,1,1]
	v_pk_fma_f32 v[48:49], v[110:111], v[140:141], v[48:49] op_sel_hi:[0,1,1]
	v_pk_fma_f32 v[50:51], v[110:111], v[142:143], v[50:51] op_sel_hi:[0,1,1]
	v_pk_fma_f32 v[28:29], v[110:111], v[144:145], v[28:29] op_sel_hi:[0,1,1]
	v_pk_fma_f32 v[32:33], v[110:111], v[146:147], v[32:33] op_sel_hi:[0,1,1]
	v_pk_fma_f32 v[34:35], v[110:111], v[148:149], v[34:35] op_sel_hi:[0,1,1]
	v_pk_fma_f32 v[36:37], v[110:111], v[150:151], v[36:37] op_sel_hi:[0,1,1]
	v_pk_fma_f32 v[38:39], v[110:111], v[152:153], v[38:39] op_sel_hi:[0,1,1]
	v_pk_fma_f32 v[40:41], v[110:111], v[154:155], v[40:41] op_sel_hi:[0,1,1]
	v_pk_fma_f32 v[42:43], v[110:111], v[156:157], v[42:43] op_sel_hi:[0,1,1]
	v_pk_fma_f32 v[20:21], v[110:111], v[158:159], v[20:21] op_sel_hi:[0,1,1]
	s_waitcnt lgkmcnt(0)
	v_pk_fma_f32 v[22:23], v[110:111], v[160:161], v[22:23] op_sel:[1,0,0] op_sel_hi:[1,1,1]
	v_pk_fma_f32 v[24:25], v[110:111], v[162:163], v[24:25] op_sel:[1,0,0] op_sel_hi:[1,1,1]
	v_pk_fma_f32 v[26:27], v[110:111], v[164:165], v[26:27] op_sel:[1,0,0] op_sel_hi:[1,1,1]
	v_pk_fma_f32 v[30:31], v[110:111], v[166:167], v[30:31] op_sel:[1,0,0] op_sel_hi:[1,1,1]
	v_pk_fma_f32 v[44:45], v[110:111], v[168:169], v[44:45] op_sel:[1,0,0] op_sel_hi:[1,1,1]
	v_pk_fma_f32 v[46:47], v[110:111], v[170:171], v[46:47] op_sel:[1,0,0] op_sel_hi:[1,1,1]
	v_pk_fma_f32 v[48:49], v[110:111], v[172:173], v[48:49] op_sel:[1,0,0] op_sel_hi:[1,1,1]
	v_pk_fma_f32 v[50:51], v[110:111], v[174:175], v[50:51] op_sel:[1,0,0] op_sel_hi:[1,1,1]
	v_pk_fma_f32 v[28:29], v[110:111], v[176:177], v[28:29] op_sel:[1,0,0] op_sel_hi:[1,1,1]
	v_pk_fma_f32 v[32:33], v[110:111], v[178:179], v[32:33] op_sel:[1,0,0] op_sel_hi:[1,1,1]
	v_pk_fma_f32 v[34:35], v[110:111], v[180:181], v[34:35] op_sel:[1,0,0] op_sel_hi:[1,1,1]
	v_pk_fma_f32 v[36:37], v[110:111], v[182:183], v[36:37] op_sel:[1,0,0] op_sel_hi:[1,1,1]
	v_pk_fma_f32 v[38:39], v[110:111], v[184:185], v[38:39] op_sel:[1,0,0] op_sel_hi:[1,1,1]
	v_pk_fma_f32 v[40:41], v[110:111], v[186:187], v[40:41] op_sel:[1,0,0] op_sel_hi:[1,1,1]
	v_pk_fma_f32 v[42:43], v[110:111], v[188:189], v[42:43] op_sel:[1,0,0] op_sel_hi:[1,1,1]
	v_pk_fma_f32 v[20:21], v[110:111], v[190:191], v[20:21] op_sel:[1,0,0] op_sel_hi:[1,1,1]
	s_cmp_eq_u32 s4, 3
	s_cbranch_scc1 .Lada_last
	v_lshl_add_u64 v[18:19], v[16:17], 0, s[0:1]
	s_add_u32 s0, s0, 0x60000
	s_addc_u32 s1, s1, 0
	global_load_dword v96, v[18:19], off
	v_lshl_add_u64 v[18:19], v[18:19], 0, s[2:3]
	global_load_dword v97, v[18:19], off
	v_lshl_add_u64 v[18:19], v[18:19], 0, s[2:3]
	global_load_dword v98, v[18:19], off
	v_lshl_add_u64 v[18:19], v[18:19], 0, s[2:3]
	global_load_dword v99, v[18:19], off
	v_lshl_add_u64 v[18:19], v[18:19], 0, s[2:3]
	global_load_dword v100, v[18:19], off
	v_lshl_add_u64 v[18:19], v[18:19], 0, s[2:3]
	global_load_dword v101, v[18:19], off
	v_lshl_add_u64 v[18:19], v[18:19], 0, s[2:3]
	global_load_dword v102, v[18:19], off
	v_lshl_add_u64 v[18:19], v[18:19], 0, s[2:3]
	global_load_dword v103, v[18:19], off
	v_lshl_add_u64 v[18:19], v[18:19], 0, s[2:3]
	global_load_dword v104, v[18:19], off
	v_lshl_add_u64 v[18:19], v[18:19], 0, s[2:3]
	global_load_dword v105, v[18:19], off
	v_lshl_add_u64 v[18:19], v[18:19], 0, s[2:3]
	global_load_dword v106, v[18:19], off
	v_lshl_add_u64 v[18:19], v[18:19], 0, s[2:3]
	global_load_dword v107, v[18:19], off
	v_lshl_add_u64 v[18:19], v[18:19], 0, s[2:3]
	global_load_dword v108, v[18:19], off
	v_lshl_add_u64 v[18:19], v[18:19], 0, s[2:3]
	global_load_dword v109, v[18:19], off
	v_lshl_add_u64 v[18:19], v[18:19], 0, s[2:3]
	global_load_dword v110, v[18:19], off
	v_lshl_add_u64 v[18:19], v[18:19], 0, s[2:3]
	global_load_dword v111, v[18:19], off
	ds_read_b128 v[128:131], v11 offset:2048
	ds_read_b128 v[132:135], v11 offset:2064
	ds_read_b128 v[136:139], v11 offset:2080
	ds_read_b128 v[140:143], v11 offset:2096
	ds_read_b128 v[144:147], v11 offset:2112
	ds_read_b128 v[148:151], v11 offset:2128
	ds_read_b128 v[152:155], v11 offset:2144
	ds_read_b128 v[156:159], v11 offset:2160
	s_waitcnt vmcnt(16)
	s_waitcnt lgkmcnt(0)
	ds_read_b128 v[160:163], v11 offset:2192
	ds_read_b128 v[164:167], v11 offset:2176
	ds_read_b128 v[168:171], v11 offset:2224
	ds_read_b128 v[172:175], v11 offset:2208
	ds_read_b128 v[176:179], v11 offset:2256
	ds_read_b128 v[180:183], v11 offset:2240
	ds_read_b128 v[184:187], v11 offset:2288
	ds_read_b128 v[188:191], v11 offset:2272
	v_pk_fma_f32 v[22:23], v[112:113], v[128:129], v[22:23] op_sel_hi:[0,1,1]
	v_pk_fma_f32 v[24:25], v[112:113], v[130:131], v[24:25] op_sel_hi:[0,1,1]
	v_pk_fma_f32 v[26:27], v[112:113], v[132:133], v[26:27] op_sel_hi:[0,1,1]
	v_pk_fma_f32 v[30:31], v[112:113], v[134:135], v[30:31] op_sel_hi:[0,1,1]
	v_pk_fma_f32 v[44:45], v[112:113], v[136:137], v[44:45] op_sel_hi:[0,1,1]
	v_pk_fma_f32 v[46:47], v[112:113], v[138:139], v[46:47] op_sel_hi:[0,1,1]
	v_pk_fma_f32 v[48:49], v[112:113], v[140:141], v[48:49] op_sel_hi:[0,1,1]
	v_pk_fma_f32 v[50:51], v[112:113], v[142:143], v[50:51] op_sel_hi:[0,1,1]
	v_pk_fma_f32 v[28:29], v[112:113], v[144:145], v[28:29] op_sel_hi:[0,1,1]
	v_pk_fma_f32 v[32:33], v[112:113], v[146:147], v[32:33] op_sel_hi:[0,1,1]
	v_pk_fma_f32 v[34:35], v[112:113], v[148:149], v[34:35] op_sel_hi:[0,1,1]
	v_pk_fma_f32 v[36:37], v[112:113], v[150:151], v[36:37] op_sel_hi:[0,1,1]
	v_pk_fma_f32 v[38:39], v[112:113], v[152:153], v[38:39] op_sel_hi:[0,1,1]
	v_pk_fma_f32 v[40:41], v[112:113], v[154:155], v[40:41] op_sel_hi:[0,1,1]
	v_pk_fma_f32 v[42:43], v[112:113], v[156:157], v[42:43] op_sel_hi:[0,1,1]
	v_pk_fma_f32 v[20:21], v[112:113], v[158:159], v[20:21] op_sel_hi:[0,1,1]
	s_waitcnt lgkmcnt(0)
	ds_read_b128 v[128:131], v11 offset:2336
	ds_read_b128 v[132:135], v11 offset:2352
	ds_read_b128 v[136:139], v11 offset:2304
	ds_read_b128 v[140:143], v11 offset:2320
	ds_read_b128 v[144:147], v11 offset:2400
	ds_read_b128 v[148:151], v11 offset:2416
	ds_read_b128 v[152:155], v11 offset:2368
	ds_read_b128 v[156:159], v11 offset:2384
	v_pk_fma_f32 v[22:23], v[112:113], v[160:161], v[22:23] op_sel:[1,0,0] op_sel_hi:[1,1,1]
	v_pk_fma_f32 v[24:25], v[112:113], v[162:163], v[24:25] op_sel:[1,0,0] op_sel_hi:[1,1,1]
	v_pk_fma_f32 v[26:27], v[112:113], v[164:165], v[26:27] op_sel:[1,0,0] op_sel_hi:[1,1,1]
	v_pk_fma_f32 v[30:31], v[112:113], v[166:167], v[30:31] op_sel:[1,0,0] op_sel_hi:[1,1,1]
	v_pk_fma_f32 v[44:45], v[112:113], v[168:169], v[44:45] op_sel:[1,0,0] op_sel_hi:[1,1,1]
	v_pk_fma_f32 v[46:47], v[112:113], v[170:171], v[46:47] op_sel:[1,0,0] op_sel_hi:[1,1,1]
	v_pk_fma_f32 v[48:49], v[112:113], v[172:173], v[48:49] op_sel:[1,0,0] op_sel_hi:[1,1,1]
	v_pk_fma_f32 v[50:51], v[112:113], v[174:175], v[50:51] op_sel:[1,0,0] op_sel_hi:[1,1,1]
	v_pk_fma_f32 v[28:29], v[112:113], v[176:177], v[28:29] op_sel:[1,0,0] op_sel_hi:[1,1,1]
	v_pk_fma_f32 v[32:33], v[112:113], v[178:179], v[32:33] op_sel:[1,0,0] op_sel_hi:[1,1,1]
	v_pk_fma_f32 v[34:35], v[112:113], v[180:181], v[34:35] op_sel:[1,0,0] op_sel_hi:[1,1,1]
	v_pk_fma_f32 v[36:37], v[112:113], v[182:183], v[36:37] op_sel:[1,0,0] op_sel_hi:[1,1,1]
	v_pk_fma_f32 v[38:39], v[112:113], v[184:185], v[38:39] op_sel:[1,0,0] op_sel_hi:[1,1,1]
	v_pk_fma_f32 v[40:41], v[112:113], v[186:187], v[40:41] op_sel:[1,0,0] op_sel_hi:[1,1,1]
	v_pk_fma_f32 v[42:43], v[112:113], v[188:189], v[42:43] op_sel:[1,0,0] op_sel_hi:[1,1,1]
	v_pk_fma_f32 v[20:21], v[112:113], v[190:191], v[20:21] op_sel:[1,0,0] op_sel_hi:[1,1,1]
	s_waitcnt lgkmcnt(0)
	ds_read_b128 v[160:163], v11 offset:2480
	ds_read_b128 v[164:167], v11 offset:2464
	ds_read_b128 v[168:171], v11 offset:2448
	ds_read_b128 v[172:175], v11 offset:2432
	ds_read_b128 v[176:179], v11 offset:2544
	ds_read_b128 v[180:183], v11 offset:2528
	ds_read_b128 v[184:187], v11 offset:2512
	ds_read_b128 v[188:191], v11 offset:2496
	v_pk_fma_f32 v[22:23], v[114:115], v[128:129], v[22:23] op_sel_hi:[0,1,1]
	v_pk_fma_f32 v[24:25], v[114:115], v[130:131], v[24:25] op_sel_hi:[0,1,1]
	v_pk_fma_f32 v[26:27], v[114:115], v[132:133], v[26:27] op_sel_hi:[0,1,1]
	v_pk_fma_f32 v[30:31], v[114:115], v[134:135], v[30:31] op_sel_hi:[0,1,1]
	v_pk_fma_f32 v[44:45], v[114:115], v[136:137], v[44:45] op_sel_hi:[0,1,1]
	v_pk_fma_f32 v[46:47], v[114:115], v[138:139], v[46:47] op_sel_hi:[0,1,1]
	v_pk_fma_f32 v[48:49], v[114:115], v[140:141], v[48:49] op_sel_hi:[0,1,1]
	v_pk_fma_f32 v[50:51], v[114:115], v[142:143], v[50:51] op_sel_hi:[0,1,1]
	v_pk_fma_f32 v[28:29], v[114:115], v[144:145], v[28:29] op_sel_hi:[0,1,1]
	v_pk_fma_f32 v[32:33], v[114:115], v[146:147], v[32:33] op_sel_hi:[0,1,1]
	v_pk_fma_f32 v[34:35], v[114:115], v[148:149], v[34:35] op_sel_hi:[0,1,1]
	v_pk_fma_f32 v[36:37], v[114:115], v[150:151], v[36:37] op_sel_hi:[0,1,1]
	v_pk_fma_f32 v[38:39], v[114:115], v[152:153], v[38:39] op_sel_hi:[0,1,1]
	v_pk_fma_f32 v[40:41], v[114:115], v[154:155], v[40:41] op_sel_hi:[0,1,1]
	v_pk_fma_f32 v[42:43], v[114:115], v[156:157], v[42:43] op_sel_hi:[0,1,1]
	v_pk_fma_f32 v[20:21], v[114:115], v[158:159], v[20:21] op_sel_hi:[0,1,1]
	s_waitcnt lgkmcnt(0)
	ds_read_b128 v[128:131], v11 offset:2624
	ds_read_b128 v[132:135], v11 offset:2640
	ds_read_b128 v[136:139], v11 offset:2656
	ds_read_b128 v[140:143], v11 offset:2672
	ds_read_b128 v[144:147], v11 offset:2560
	ds_read_b128 v[148:151], v11 offset:2576
	ds_read_b128 v[152:155], v11 offset:2592
	ds_read_b128 v[156:159], v11 offset:2608
	v_pk_fma_f32 v[22:23], v[114:115], v[160:161], v[22:23] op_sel:[1,0,0] op_sel_hi:[1,1,1]
	v_pk_fma_f32 v[24:25], v[114:115], v[162:163], v[24:25] op_sel:[1,0,0] op_sel_hi:[1,1,1]
	v_pk_fma_f32 v[26:27], v[114:115], v[164:165], v[26:27] op_sel:[1,0,0] op_sel_hi:[1,1,1]
	v_pk_fma_f32 v[30:31], v[114:115], v[166:167], v[30:31] op_sel:[1,0,0] op_sel_hi:[1,1,1]
	v_pk_fma_f32 v[44:45], v[114:115], v[168:169], v[44:45] op_sel:[1,0,0] op_sel_hi:[1,1,1]
	v_pk_fma_f32 v[46:47], v[114:115], v[170:171], v[46:47] op_sel:[1,0,0] op_sel_hi:[1,1,1]
	v_pk_fma_f32 v[48:49], v[114:115], v[172:173], v[48:49] op_sel:[1,0,0] op_sel_hi:[1,1,1]
	v_pk_fma_f32 v[50:51], v[114:115], v[174:175], v[50:51] op_sel:[1,0,0] op_sel_hi:[1,1,1]
	v_pk_fma_f32 v[28:29], v[114:115], v[176:177], v[28:29] op_sel:[1,0,0] op_sel_hi:[1,1,1]
	v_pk_fma_f32 v[32:33], v[114:115], v[178:179], v[32:33] op_sel:[1,0,0] op_sel_hi:[1,1,1]
	v_pk_fma_f32 v[34:35], v[114:115], v[180:181], v[34:35] op_sel:[1,0,0] op_sel_hi:[1,1,1]
	v_pk_fma_f32 v[36:37], v[114:115], v[182:183], v[36:37] op_sel:[1,0,0] op_sel_hi:[1,1,1]
	v_pk_fma_f32 v[38:39], v[114:115], v[184:185], v[38:39] op_sel:[1,0,0] op_sel_hi:[1,1,1]
	v_pk_fma_f32 v[40:41], v[114:115], v[186:187], v[40:41] op_sel:[1,0,0] op_sel_hi:[1,1,1]
	v_pk_fma_f32 v[42:43], v[114:115], v[188:189], v[42:43] op_sel:[1,0,0] op_sel_hi:[1,1,1]
	v_pk_fma_f32 v[20:21], v[114:115], v[190:191], v[20:21] op_sel:[1,0,0] op_sel_hi:[1,1,1]
	s_waitcnt lgkmcnt(0)
	ds_read_b128 v[160:163], v11 offset:2768
	ds_read_b128 v[164:167], v11 offset:2752
	ds_read_b128 v[168:171], v11 offset:2800
	ds_read_b128 v[172:175], v11 offset:2784
	ds_read_b128 v[176:179], v11 offset:2704
	ds_read_b128 v[180:183], v11 offset:2688
	ds_read_b128 v[184:187], v11 offset:2736
	ds_read_b128 v[188:191], v11 offset:2720
	v_pk_fma_f32 v[22:23], v[116:117], v[128:129], v[22:23] op_sel_hi:[0,1,1]
	v_pk_fma_f32 v[24:25], v[116:117], v[130:131], v[24:25] op_sel_hi:[0,1,1]
	v_pk_fma_f32 v[26:27], v[116:117], v[132:133], v[26:27] op_sel_hi:[0,1,1]
	v_pk_fma_f32 v[30:31], v[116:117], v[134:135], v[30:31] op_sel_hi:[0,1,1]
	v_pk_fma_f32 v[44:45], v[116:117], v[136:137], v[44:45] op_sel_hi:[0,1,1]
	v_pk_fma_f32 v[46:47], v[116:117], v[138:139], v[46:47] op_sel_hi:[0,1,1]
	v_pk_fma_f32 v[48:49], v[116:117], v[140:141], v[48:49] op_sel_hi:[0,1,1]
	v_pk_fma_f32 v[50:51], v[116:117], v[142:143], v[50:51] op_sel_hi:[0,1,1]
	v_pk_fma_f32 v[28:29], v[116:117], v[144:145], v[28:29] op_sel_hi:[0,1,1]
	v_pk_fma_f32 v[32:33], v[116:117], v[146:147], v[32:33] op_sel_hi:[0,1,1]
	v_pk_fma_f32 v[34:35], v[116:117], v[148:149], v[34:35] op_sel_hi:[0,1,1]
	v_pk_fma_f32 v[36:37], v[116:117], v[150:151], v[36:37] op_sel_hi:[0,1,1]
	v_pk_fma_f32 v[38:39], v[116:117], v[152:153], v[38:39] op_sel_hi:[0,1,1]
	v_pk_fma_f32 v[40:41], v[116:117], v[154:155], v[40:41] op_sel_hi:[0,1,1]
	v_pk_fma_f32 v[42:43], v[116:117], v[156:157], v[42:43] op_sel_hi:[0,1,1]
	v_pk_fma_f32 v[20:21], v[116:117], v[158:159], v[20:21] op_sel_hi:[0,1,1]
	s_waitcnt lgkmcnt(0)
	ds_read_b128 v[128:131], v11 offset:2912
	ds_read_b128 v[132:135], v11 offset:2928
	ds_read_b128 v[136:139], v11 offset:2880
	ds_read_b128 v[140:143], v11 offset:2896
	ds_read_b128 v[144:147], v11 offset:2848
	ds_read_b128 v[148:151], v11 offset:2864
	ds_read_b128 v[152:155], v11 offset:2816
	ds_read_b128 v[156:159], v11 offset:2832
	v_pk_fma_f32 v[22:23], v[116:117], v[160:161], v[22:23] op_sel:[1,0,0] op_sel_hi:[1,1,1]
	v_pk_fma_f32 v[24:25], v[116:117], v[162:163], v[24:25] op_sel:[1,0,0] op_sel_hi:[1,1,1]
	v_pk_fma_f32 v[26:27], v[116:117], v[164:165], v[26:27] op_sel:[1,0,0] op_sel_hi:[1,1,1]
	v_pk_fma_f32 v[30:31], v[116:117], v[166:167], v[30:31] op_sel:[1,0,0] op_sel_hi:[1,1,1]
	v_pk_fma_f32 v[44:45], v[116:117], v[168:169], v[44:45] op_sel:[1,0,0] op_sel_hi:[1,1,1]
	v_pk_fma_f32 v[46:47], v[116:117], v[170:171], v[46:47] op_sel:[1,0,0] op_sel_hi:[1,1,1]
	v_pk_fma_f32 v[48:49], v[116:117], v[172:173], v[48:49] op_sel:[1,0,0] op_sel_hi:[1,1,1]
	v_pk_fma_f32 v[50:51], v[116:117], v[174:175], v[50:51] op_sel:[1,0,0] op_sel_hi:[1,1,1]
	v_pk_fma_f32 v[28:29], v[116:117], v[176:177], v[28:29] op_sel:[1,0,0] op_sel_hi:[1,1,1]
	v_pk_fma_f32 v[32:33], v[116:117], v[178:179], v[32:33] op_sel:[1,0,0] op_sel_hi:[1,1,1]
	v_pk_fma_f32 v[34:35], v[116:117], v[180:181], v[34:35] op_sel:[1,0,0] op_sel_hi:[1,1,1]
	v_pk_fma_f32 v[36:37], v[116:117], v[182:183], v[36:37] op_sel:[1,0,0] op_sel_hi:[1,1,1]
	v_pk_fma_f32 v[38:39], v[116:117], v[184:185], v[38:39] op_sel:[1,0,0] op_sel_hi:[1,1,1]
	v_pk_fma_f32 v[40:41], v[116:117], v[186:187], v[40:41] op_sel:[1,0,0] op_sel_hi:[1,1,1]
	v_pk_fma_f32 v[42:43], v[116:117], v[188:189], v[42:43] op_sel:[1,0,0] op_sel_hi:[1,1,1]
	v_pk_fma_f32 v[20:21], v[116:117], v[190:191], v[20:21] op_sel:[1,0,0] op_sel_hi:[1,1,1]
	s_waitcnt lgkmcnt(0)
	ds_read_b128 v[160:163], v11 offset:3056
	ds_read_b128 v[164:167], v11 offset:3040
	ds_read_b128 v[168:171], v11 offset:3024
	ds_read_b128 v[172:175], v11 offset:3008
	ds_read_b128 v[176:179], v11 offset:2992
	ds_read_b128 v[180:183], v11 offset:2976
	ds_read_b128 v[184:187], v11 offset:2960
	ds_read_b128 v[188:191], v11 offset:2944
	v_pk_fma_f32 v[22:23], v[118:119], v[128:129], v[22:23] op_sel_hi:[0,1,1]
	v_pk_fma_f32 v[24:25], v[118:119], v[130:131], v[24:25] op_sel_hi:[0,1,1]
	v_pk_fma_f32 v[26:27], v[118:119], v[132:133], v[26:27] op_sel_hi:[0,1,1]
	v_pk_fma_f32 v[30:31], v[118:119], v[134:135], v[30:31] op_sel_hi:[0,1,1]
	v_pk_fma_f32 v[44:45], v[118:119], v[136:137], v[44:45] op_sel_hi:[0,1,1]
	v_pk_fma_f32 v[46:47], v[118:119], v[138:139], v[46:47] op_sel_hi:[0,1,1]
	v_pk_fma_f32 v[48:49], v[118:119], v[140:141], v[48:49] op_sel_hi:[0,1,1]
	v_pk_fma_f32 v[50:51], v[118:119], v[142:143], v[50:51] op_sel_hi:[0,1,1]
	v_pk_fma_f32 v[28:29], v[118:119], v[144:145], v[28:29] op_sel_hi:[0,1,1]
	v_pk_fma_f32 v[32:33], v[118:119], v[146:147], v[32:33] op_sel_hi:[0,1,1]
	v_pk_fma_f32 v[34:35], v[118:119], v[148:149], v[34:35] op_sel_hi:[0,1,1]
	v_pk_fma_f32 v[36:37], v[118:119], v[150:151], v[36:37] op_sel_hi:[0,1,1]
	v_pk_fma_f32 v[38:39], v[118:119], v[152:153], v[38:39] op_sel_hi:[0,1,1]
	v_pk_fma_f32 v[40:41], v[118:119], v[154:155], v[40:41] op_sel_hi:[0,1,1]
	v_pk_fma_f32 v[42:43], v[118:119], v[156:157], v[42:43] op_sel_hi:[0,1,1]
	v_pk_fma_f32 v[20:21], v[118:119], v[158:159], v[20:21] op_sel_hi:[0,1,1]
	s_waitcnt lgkmcnt(0)
	ds_read_b128 v[128:131], v11 offset:3072
	ds_read_b128 v[132:135], v11 offset:3088
	ds_read_b128 v[136:139], v11 offset:3104
	ds_read_b128 v[140:143], v11 offset:3120
	ds_read_b128 v[144:147], v11 offset:3136
	ds_read_b128 v[148:151], v11 offset:3152
	ds_read_b128 v[152:155], v11 offset:3168
	ds_read_b128 v[156:159], v11 offset:3184
	v_pk_fma_f32 v[22:23], v[118:119], v[160:161], v[22:23] op_sel:[1,0,0] op_sel_hi:[1,1,1]
	v_pk_fma_f32 v[24:25], v[118:119], v[162:163], v[24:25] op_sel:[1,0,0] op_sel_hi:[1,1,1]
	v_pk_fma_f32 v[26:27], v[118:119], v[164:165], v[26:27] op_sel:[1,0,0] op_sel_hi:[1,1,1]
	v_pk_fma_f32 v[30:31], v[118:119], v[166:167], v[30:31] op_sel:[1,0,0] op_sel_hi:[1,1,1]
	v_pk_fma_f32 v[44:45], v[118:119], v[168:169], v[44:45] op_sel:[1,0,0] op_sel_hi:[1,1,1]
	v_pk_fma_f32 v[46:47], v[118:119], v[170:171], v[46:47] op_sel:[1,0,0] op_sel_hi:[1,1,1]
	v_pk_fma_f32 v[48:49], v[118:119], v[172:173], v[48:49] op_sel:[1,0,0] op_sel_hi:[1,1,1]
	v_pk_fma_f32 v[50:51], v[118:119], v[174:175], v[50:51] op_sel:[1,0,0] op_sel_hi:[1,1,1]
	v_pk_fma_f32 v[28:29], v[118:119], v[176:177], v[28:29] op_sel:[1,0,0] op_sel_hi:[1,1,1]
	v_pk_fma_f32 v[32:33], v[118:119], v[178:179], v[32:33] op_sel:[1,0,0] op_sel_hi:[1,1,1]
	v_pk_fma_f32 v[34:35], v[118:119], v[180:181], v[34:35] op_sel:[1,0,0] op_sel_hi:[1,1,1]
	v_pk_fma_f32 v[36:37], v[118:119], v[182:183], v[36:37] op_sel:[1,0,0] op_sel_hi:[1,1,1]
	v_pk_fma_f32 v[38:39], v[118:119], v[184:185], v[38:39] op_sel:[1,0,0] op_sel_hi:[1,1,1]
	v_pk_fma_f32 v[40:41], v[118:119], v[186:187], v[40:41] op_sel:[1,0,0] op_sel_hi:[1,1,1]
	v_pk_fma_f32 v[42:43], v[118:119], v[188:189], v[42:43] op_sel:[1,0,0] op_sel_hi:[1,1,1]
	v_pk_fma_f32 v[20:21], v[118:119], v[190:191], v[20:21] op_sel:[1,0,0] op_sel_hi:[1,1,1]
	s_waitcnt lgkmcnt(0)
	ds_read_b128 v[160:163], v11 offset:3216
	ds_read_b128 v[164:167], v11 offset:3200
	ds_read_b128 v[168:171], v11 offset:3248
	ds_read_b128 v[172:175], v11 offset:3232
	ds_read_b128 v[176:179], v11 offset:3280
	ds_read_b128 v[180:183], v11 offset:3264
	ds_read_b128 v[184:187], v11 offset:3312
	ds_read_b128 v[188:191], v11 offset:3296
	v_pk_fma_f32 v[22:23], v[120:121], v[128:129], v[22:23] op_sel_hi:[0,1,1]
	v_pk_fma_f32 v[24:25], v[120:121], v[130:131], v[24:25] op_sel_hi:[0,1,1]
	v_pk_fma_f32 v[26:27], v[120:121], v[132:133], v[26:27] op_sel_hi:[0,1,1]
	v_pk_fma_f32 v[30:31], v[120:121], v[134:135], v[30:31] op_sel_hi:[0,1,1]
	v_pk_fma_f32 v[44:45], v[120:121], v[136:137], v[44:45] op_sel_hi:[0,1,1]
	v_pk_fma_f32 v[46:47], v[120:121], v[138:139], v[46:47] op_sel_hi:[0,1,1]
	v_pk_fma_f32 v[48:49], v[120:121], v[140:141], v[48:49] op_sel_hi:[0,1,1]
	v_pk_fma_f32 v[50:51], v[120:121], v[142:143], v[50:51] op_sel_hi:[0,1,1]
	v_pk_fma_f32 v[28:29], v[120:121], v[144:145], v[28:29] op_sel_hi:[0,1,1]
	v_pk_fma_f32 v[32:33], v[120:121], v[146:147], v[32:33] op_sel_hi:[0,1,1]
	v_pk_fma_f32 v[34:35], v[120:121], v[148:149], v[34:35] op_sel_hi:[0,1,1]
	v_pk_fma_f32 v[36:37], v[120:121], v[150:151], v[36:37] op_sel_hi:[0,1,1]
	v_pk_fma_f32 v[38:39], v[120:121], v[152:153], v[38:39] op_sel_hi:[0,1,1]
	v_pk_fma_f32 v[40:41], v[120:121], v[154:155], v[40:41] op_sel_hi:[0,1,1]
	v_pk_fma_f32 v[42:43], v[120:121], v[156:157], v[42:43] op_sel_hi:[0,1,1]
	v_pk_fma_f32 v[20:21], v[120:121], v[158:159], v[20:21] op_sel_hi:[0,1,1]
	s_waitcnt lgkmcnt(0)
	ds_read_b128 v[128:131], v11 offset:3360
	ds_read_b128 v[132:135], v11 offset:3376
	ds_read_b128 v[136:139], v11 offset:3328
	ds_read_b128 v[140:143], v11 offset:3344
	ds_read_b128 v[144:147], v11 offset:3424
	ds_read_b128 v[148:151], v11 offset:3440
	ds_read_b128 v[152:155], v11 offset:3392
	ds_read_b128 v[156:159], v11 offset:3408
	v_pk_fma_f32 v[22:23], v[120:121], v[160:161], v[22:23] op_sel:[1,0,0] op_sel_hi:[1,1,1]
	v_pk_fma_f32 v[24:25], v[120:121], v[162:163], v[24:25] op_sel:[1,0,0] op_sel_hi:[1,1,1]
	v_pk_fma_f32 v[26:27], v[120:121], v[164:165], v[26:27] op_sel:[1,0,0] op_sel_hi:[1,1,1]
	v_pk_fma_f32 v[30:31], v[120:121], v[166:167], v[30:31] op_sel:[1,0,0] op_sel_hi:[1,1,1]
	v_pk_fma_f32 v[44:45], v[120:121], v[168:169], v[44:45] op_sel:[1,0,0] op_sel_hi:[1,1,1]
	v_pk_fma_f32 v[46:47], v[120:121], v[170:171], v[46:47] op_sel:[1,0,0] op_sel_hi:[1,1,1]
	v_pk_fma_f32 v[48:49], v[120:121], v[172:173], v[48:49] op_sel:[1,0,0] op_sel_hi:[1,1,1]
	v_pk_fma_f32 v[50:51], v[120:121], v[174:175], v[50:51] op_sel:[1,0,0] op_sel_hi:[1,1,1]
	v_pk_fma_f32 v[28:29], v[120:121], v[176:177], v[28:29] op_sel:[1,0,0] op_sel_hi:[1,1,1]
	v_pk_fma_f32 v[32:33], v[120:121], v[178:179], v[32:33] op_sel:[1,0,0] op_sel_hi:[1,1,1]
	v_pk_fma_f32 v[34:35], v[120:121], v[180:181], v[34:35] op_sel:[1,0,0] op_sel_hi:[1,1,1]
	v_pk_fma_f32 v[36:37], v[120:121], v[182:183], v[36:37] op_sel:[1,0,0] op_sel_hi:[1,1,1]
	v_pk_fma_f32 v[38:39], v[120:121], v[184:185], v[38:39] op_sel:[1,0,0] op_sel_hi:[1,1,1]
	v_pk_fma_f32 v[40:41], v[120:121], v[186:187], v[40:41] op_sel:[1,0,0] op_sel_hi:[1,1,1]
	v_pk_fma_f32 v[42:43], v[120:121], v[188:189], v[42:43] op_sel:[1,0,0] op_sel_hi:[1,1,1]
	v_pk_fma_f32 v[20:21], v[120:121], v[190:191], v[20:21] op_sel:[1,0,0] op_sel_hi:[1,1,1]
	s_waitcnt lgkmcnt(0)
	ds_read_b128 v[160:163], v11 offset:3504
	ds_read_b128 v[164:167], v11 offset:3488
	ds_read_b128 v[168:171], v11 offset:3472
	ds_read_b128 v[172:175], v11 offset:3456
	ds_read_b128 v[176:179], v11 offset:3568
	ds_read_b128 v[180:183], v11 offset:3552
	ds_read_b128 v[184:187], v11 offset:3536
	ds_read_b128 v[188:191], v11 offset:3520
	v_pk_fma_f32 v[22:23], v[122:123], v[128:129], v[22:23] op_sel_hi:[0,1,1]
	v_pk_fma_f32 v[24:25], v[122:123], v[130:131], v[24:25] op_sel_hi:[0,1,1]
	v_pk_fma_f32 v[26:27], v[122:123], v[132:133], v[26:27] op_sel_hi:[0,1,1]
	v_pk_fma_f32 v[30:31], v[122:123], v[134:135], v[30:31] op_sel_hi:[0,1,1]
	v_pk_fma_f32 v[44:45], v[122:123], v[136:137], v[44:45] op_sel_hi:[0,1,1]
	v_pk_fma_f32 v[46:47], v[122:123], v[138:139], v[46:47] op_sel_hi:[0,1,1]
	v_pk_fma_f32 v[48:49], v[122:123], v[140:141], v[48:49] op_sel_hi:[0,1,1]
	v_pk_fma_f32 v[50:51], v[122:123], v[142:143], v[50:51] op_sel_hi:[0,1,1]
	v_pk_fma_f32 v[28:29], v[122:123], v[144:145], v[28:29] op_sel_hi:[0,1,1]
	v_pk_fma_f32 v[32:33], v[122:123], v[146:147], v[32:33] op_sel_hi:[0,1,1]
	v_pk_fma_f32 v[34:35], v[122:123], v[148:149], v[34:35] op_sel_hi:[0,1,1]
	v_pk_fma_f32 v[36:37], v[122:123], v[150:151], v[36:37] op_sel_hi:[0,1,1]
	v_pk_fma_f32 v[38:39], v[122:123], v[152:153], v[38:39] op_sel_hi:[0,1,1]
	v_pk_fma_f32 v[40:41], v[122:123], v[154:155], v[40:41] op_sel_hi:[0,1,1]
	v_pk_fma_f32 v[42:43], v[122:123], v[156:157], v[42:43] op_sel_hi:[0,1,1]
	v_pk_fma_f32 v[20:21], v[122:123], v[158:159], v[20:21] op_sel_hi:[0,1,1]
	s_waitcnt lgkmcnt(0)
	ds_read_b128 v[128:131], v11 offset:3648
	ds_read_b128 v[132:135], v11 offset:3664
	ds_read_b128 v[136:139], v11 offset:3680
	ds_read_b128 v[140:143], v11 offset:3696
	ds_read_b128 v[144:147], v11 offset:3584
	ds_read_b128 v[148:151], v11 offset:3600
	ds_read_b128 v[152:155], v11 offset:3616
	ds_read_b128 v[156:159], v11 offset:3632
	v_pk_fma_f32 v[22:23], v[122:123], v[160:161], v[22:23] op_sel:[1,0,0] op_sel_hi:[1,1,1]
	v_pk_fma_f32 v[24:25], v[122:123], v[162:163], v[24:25] op_sel:[1,0,0] op_sel_hi:[1,1,1]
	v_pk_fma_f32 v[26:27], v[122:123], v[164:165], v[26:27] op_sel:[1,0,0] op_sel_hi:[1,1,1]
	v_pk_fma_f32 v[30:31], v[122:123], v[166:167], v[30:31] op_sel:[1,0,0] op_sel_hi:[1,1,1]
	v_pk_fma_f32 v[44:45], v[122:123], v[168:169], v[44:45] op_sel:[1,0,0] op_sel_hi:[1,1,1]
	v_pk_fma_f32 v[46:47], v[122:123], v[170:171], v[46:47] op_sel:[1,0,0] op_sel_hi:[1,1,1]
	v_pk_fma_f32 v[48:49], v[122:123], v[172:173], v[48:49] op_sel:[1,0,0] op_sel_hi:[1,1,1]
	v_pk_fma_f32 v[50:51], v[122:123], v[174:175], v[50:51] op_sel:[1,0,0] op_sel_hi:[1,1,1]
	v_pk_fma_f32 v[28:29], v[122:123], v[176:177], v[28:29] op_sel:[1,0,0] op_sel_hi:[1,1,1]
	v_pk_fma_f32 v[32:33], v[122:123], v[178:179], v[32:33] op_sel:[1,0,0] op_sel_hi:[1,1,1]
	v_pk_fma_f32 v[34:35], v[122:123], v[180:181], v[34:35] op_sel:[1,0,0] op_sel_hi:[1,1,1]
	v_pk_fma_f32 v[36:37], v[122:123], v[182:183], v[36:37] op_sel:[1,0,0] op_sel_hi:[1,1,1]
	v_pk_fma_f32 v[38:39], v[122:123], v[184:185], v[38:39] op_sel:[1,0,0] op_sel_hi:[1,1,1]
	v_pk_fma_f32 v[40:41], v[122:123], v[186:187], v[40:41] op_sel:[1,0,0] op_sel_hi:[1,1,1]
	v_pk_fma_f32 v[42:43], v[122:123], v[188:189], v[42:43] op_sel:[1,0,0] op_sel_hi:[1,1,1]
	v_pk_fma_f32 v[20:21], v[122:123], v[190:191], v[20:21] op_sel:[1,0,0] op_sel_hi:[1,1,1]
	s_waitcnt lgkmcnt(0)
	ds_read_b128 v[160:163], v11 offset:3792
	ds_read_b128 v[164:167], v11 offset:3776
	ds_read_b128 v[168:171], v11 offset:3824
	ds_read_b128 v[172:175], v11 offset:3808
	ds_read_b128 v[176:179], v11 offset:3728
	ds_read_b128 v[180:183], v11 offset:3712
	ds_read_b128 v[184:187], v11 offset:3760
	ds_read_b128 v[188:191], v11 offset:3744
	v_pk_fma_f32 v[22:23], v[124:125], v[128:129], v[22:23] op_sel_hi:[0,1,1]
	v_pk_fma_f32 v[24:25], v[124:125], v[130:131], v[24:25] op_sel_hi:[0,1,1]
	v_pk_fma_f32 v[26:27], v[124:125], v[132:133], v[26:27] op_sel_hi:[0,1,1]
	v_pk_fma_f32 v[30:31], v[124:125], v[134:135], v[30:31] op_sel_hi:[0,1,1]
	v_pk_fma_f32 v[44:45], v[124:125], v[136:137], v[44:45] op_sel_hi:[0,1,1]
	v_pk_fma_f32 v[46:47], v[124:125], v[138:139], v[46:47] op_sel_hi:[0,1,1]
	v_pk_fma_f32 v[48:49], v[124:125], v[140:141], v[48:49] op_sel_hi:[0,1,1]
	v_pk_fma_f32 v[50:51], v[124:125], v[142:143], v[50:51] op_sel_hi:[0,1,1]
	v_pk_fma_f32 v[28:29], v[124:125], v[144:145], v[28:29] op_sel_hi:[0,1,1]
	v_pk_fma_f32 v[32:33], v[124:125], v[146:147], v[32:33] op_sel_hi:[0,1,1]
	v_pk_fma_f32 v[34:35], v[124:125], v[148:149], v[34:35] op_sel_hi:[0,1,1]
	v_pk_fma_f32 v[36:37], v[124:125], v[150:151], v[36:37] op_sel_hi:[0,1,1]
	v_pk_fma_f32 v[38:39], v[124:125], v[152:153], v[38:39] op_sel_hi:[0,1,1]
	v_pk_fma_f32 v[40:41], v[124:125], v[154:155], v[40:41] op_sel_hi:[0,1,1]
	v_pk_fma_f32 v[42:43], v[124:125], v[156:157], v[42:43] op_sel_hi:[0,1,1]
	v_pk_fma_f32 v[20:21], v[124:125], v[158:159], v[20:21] op_sel_hi:[0,1,1]
	s_waitcnt lgkmcnt(0)
	ds_read_b128 v[128:131], v11 offset:3936
	ds_read_b128 v[132:135], v11 offset:3952
	ds_read_b128 v[136:139], v11 offset:3904
	ds_read_b128 v[140:143], v11 offset:3920
	ds_read_b128 v[144:147], v11 offset:3872
	ds_read_b128 v[148:151], v11 offset:3888
	ds_read_b128 v[152:155], v11 offset:3840
	ds_read_b128 v[156:159], v11 offset:3856
	v_pk_fma_f32 v[22:23], v[124:125], v[160:161], v[22:23] op_sel:[1,0,0] op_sel_hi:[1,1,1]
	v_pk_fma_f32 v[24:25], v[124:125], v[162:163], v[24:25] op_sel:[1,0,0] op_sel_hi:[1,1,1]
	v_pk_fma_f32 v[26:27], v[124:125], v[164:165], v[26:27] op_sel:[1,0,0] op_sel_hi:[1,1,1]
	v_pk_fma_f32 v[30:31], v[124:125], v[166:167], v[30:31] op_sel:[1,0,0] op_sel_hi:[1,1,1]
	v_pk_fma_f32 v[44:45], v[124:125], v[168:169], v[44:45] op_sel:[1,0,0] op_sel_hi:[1,1,1]
	v_pk_fma_f32 v[46:47], v[124:125], v[170:171], v[46:47] op_sel:[1,0,0] op_sel_hi:[1,1,1]
	v_pk_fma_f32 v[48:49], v[124:125], v[172:173], v[48:49] op_sel:[1,0,0] op_sel_hi:[1,1,1]
	v_pk_fma_f32 v[50:51], v[124:125], v[174:175], v[50:51] op_sel:[1,0,0] op_sel_hi:[1,1,1]
	v_pk_fma_f32 v[28:29], v[124:125], v[176:177], v[28:29] op_sel:[1,0,0] op_sel_hi:[1,1,1]
	v_pk_fma_f32 v[32:33], v[124:125], v[178:179], v[32:33] op_sel:[1,0,0] op_sel_hi:[1,1,1]
	v_pk_fma_f32 v[34:35], v[124:125], v[180:181], v[34:35] op_sel:[1,0,0] op_sel_hi:[1,1,1]
	v_pk_fma_f32 v[36:37], v[124:125], v[182:183], v[36:37] op_sel:[1,0,0] op_sel_hi:[1,1,1]
	v_pk_fma_f32 v[38:39], v[124:125], v[184:185], v[38:39] op_sel:[1,0,0] op_sel_hi:[1,1,1]
	v_pk_fma_f32 v[40:41], v[124:125], v[186:187], v[40:41] op_sel:[1,0,0] op_sel_hi:[1,1,1]
	v_pk_fma_f32 v[42:43], v[124:125], v[188:189], v[42:43] op_sel:[1,0,0] op_sel_hi:[1,1,1]
	v_pk_fma_f32 v[20:21], v[124:125], v[190:191], v[20:21] op_sel:[1,0,0] op_sel_hi:[1,1,1]
	s_waitcnt lgkmcnt(0)
	ds_read_b128 v[160:163], v11 offset:4080
	ds_read_b128 v[164:167], v11 offset:4064
	ds_read_b128 v[168:171], v11 offset:4048
	ds_read_b128 v[172:175], v11 offset:4032
	ds_read_b128 v[176:179], v11 offset:4016
	ds_read_b128 v[180:183], v11 offset:4000
	ds_read_b128 v[184:187], v11 offset:3984
	ds_read_b128 v[188:191], v11 offset:3968
	v_pk_fma_f32 v[22:23], v[126:127], v[128:129], v[22:23] op_sel_hi:[0,1,1]
	v_pk_fma_f32 v[24:25], v[126:127], v[130:131], v[24:25] op_sel_hi:[0,1,1]
	v_pk_fma_f32 v[26:27], v[126:127], v[132:133], v[26:27] op_sel_hi:[0,1,1]
	v_pk_fma_f32 v[30:31], v[126:127], v[134:135], v[30:31] op_sel_hi:[0,1,1]
	v_pk_fma_f32 v[44:45], v[126:127], v[136:137], v[44:45] op_sel_hi:[0,1,1]
	v_pk_fma_f32 v[46:47], v[126:127], v[138:139], v[46:47] op_sel_hi:[0,1,1]
	v_pk_fma_f32 v[48:49], v[126:127], v[140:141], v[48:49] op_sel_hi:[0,1,1]
	v_pk_fma_f32 v[50:51], v[126:127], v[142:143], v[50:51] op_sel_hi:[0,1,1]
	v_pk_fma_f32 v[28:29], v[126:127], v[144:145], v[28:29] op_sel_hi:[0,1,1]
	v_pk_fma_f32 v[32:33], v[126:127], v[146:147], v[32:33] op_sel_hi:[0,1,1]
	v_pk_fma_f32 v[34:35], v[126:127], v[148:149], v[34:35] op_sel_hi:[0,1,1]
	v_pk_fma_f32 v[36:37], v[126:127], v[150:151], v[36:37] op_sel_hi:[0,1,1]
	v_pk_fma_f32 v[38:39], v[126:127], v[152:153], v[38:39] op_sel_hi:[0,1,1]
	v_pk_fma_f32 v[40:41], v[126:127], v[154:155], v[40:41] op_sel_hi:[0,1,1]
	v_pk_fma_f32 v[42:43], v[126:127], v[156:157], v[42:43] op_sel_hi:[0,1,1]
	v_pk_fma_f32 v[20:21], v[126:127], v[158:159], v[20:21] op_sel_hi:[0,1,1]
	s_waitcnt lgkmcnt(0)
	v_pk_fma_f32 v[22:23], v[126:127], v[160:161], v[22:23] op_sel:[1,0,0] op_sel_hi:[1,1,1]
	v_pk_fma_f32 v[24:25], v[126:127], v[162:163], v[24:25] op_sel:[1,0,0] op_sel_hi:[1,1,1]
	v_pk_fma_f32 v[26:27], v[126:127], v[164:165], v[26:27] op_sel:[1,0,0] op_sel_hi:[1,1,1]
	v_pk_fma_f32 v[30:31], v[126:127], v[166:167], v[30:31] op_sel:[1,0,0] op_sel_hi:[1,1,1]
	v_pk_fma_f32 v[44:45], v[126:127], v[168:169], v[44:45] op_sel:[1,0,0] op_sel_hi:[1,1,1]
	v_pk_fma_f32 v[46:47], v[126:127], v[170:171], v[46:47] op_sel:[1,0,0] op_sel_hi:[1,1,1]
	v_pk_fma_f32 v[48:49], v[126:127], v[172:173], v[48:49] op_sel:[1,0,0] op_sel_hi:[1,1,1]
	v_pk_fma_f32 v[50:51], v[126:127], v[174:175], v[50:51] op_sel:[1,0,0] op_sel_hi:[1,1,1]
	v_pk_fma_f32 v[28:29], v[126:127], v[176:177], v[28:29] op_sel:[1,0,0] op_sel_hi:[1,1,1]
	v_pk_fma_f32 v[32:33], v[126:127], v[178:179], v[32:33] op_sel:[1,0,0] op_sel_hi:[1,1,1]
	v_pk_fma_f32 v[34:35], v[126:127], v[180:181], v[34:35] op_sel:[1,0,0] op_sel_hi:[1,1,1]
	v_pk_fma_f32 v[36:37], v[126:127], v[182:183], v[36:37] op_sel:[1,0,0] op_sel_hi:[1,1,1]
	v_pk_fma_f32 v[38:39], v[126:127], v[184:185], v[38:39] op_sel:[1,0,0] op_sel_hi:[1,1,1]
	v_pk_fma_f32 v[40:41], v[126:127], v[186:187], v[40:41] op_sel:[1,0,0] op_sel_hi:[1,1,1]
	v_pk_fma_f32 v[42:43], v[126:127], v[188:189], v[42:43] op_sel:[1,0,0] op_sel_hi:[1,1,1]
	v_pk_fma_f32 v[20:21], v[126:127], v[190:191], v[20:21] op_sel:[1,0,0] op_sel_hi:[1,1,1]
	v_add_u32_e32 v11, 0x1000, v11
	s_add_i32 s4, s4, 1
	s_branch .Lada_loop
.Lada_last:
	ds_read_b128 v[128:131], v11 offset:2048
	ds_read_b128 v[132:135], v11 offset:2064
	ds_read_b128 v[136:139], v11 offset:2080
	ds_read_b128 v[140:143], v11 offset:2096
	ds_read_b128 v[144:147], v11 offset:2112
	ds_read_b128 v[148:151], v11 offset:2128
	ds_read_b128 v[152:155], v11 offset:2144
	ds_read_b128 v[156:159], v11 offset:2160
	s_waitcnt vmcnt(0)
	s_waitcnt lgkmcnt(0)
	ds_read_b128 v[160:163], v11 offset:2192
	ds_read_b128 v[164:167], v11 offset:2176
	ds_read_b128 v[168:171], v11 offset:2224
	ds_read_b128 v[172:175], v11 offset:2208
	ds_read_b128 v[176:179], v11 offset:2256
	ds_read_b128 v[180:183], v11 offset:2240
	ds_read_b128 v[184:187], v11 offset:2288
	ds_read_b128 v[188:191], v11 offset:2272
	v_pk_fma_f32 v[22:23], v[112:113], v[128:129], v[22:23] op_sel_hi:[0,1,1]
	v_pk_fma_f32 v[24:25], v[112:113], v[130:131], v[24:25] op_sel_hi:[0,1,1]
	v_pk_fma_f32 v[26:27], v[112:113], v[132:133], v[26:27] op_sel_hi:[0,1,1]
	v_pk_fma_f32 v[30:31], v[112:113], v[134:135], v[30:31] op_sel_hi:[0,1,1]
	v_pk_fma_f32 v[44:45], v[112:113], v[136:137], v[44:45] op_sel_hi:[0,1,1]
	v_pk_fma_f32 v[46:47], v[112:113], v[138:139], v[46:47] op_sel_hi:[0,1,1]
	v_pk_fma_f32 v[48:49], v[112:113], v[140:141], v[48:49] op_sel_hi:[0,1,1]
	v_pk_fma_f32 v[50:51], v[112:113], v[142:143], v[50:51] op_sel_hi:[0,1,1]
	v_pk_fma_f32 v[28:29], v[112:113], v[144:145], v[28:29] op_sel_hi:[0,1,1]
	v_pk_fma_f32 v[32:33], v[112:113], v[146:147], v[32:33] op_sel_hi:[0,1,1]
	v_pk_fma_f32 v[34:35], v[112:113], v[148:149], v[34:35] op_sel_hi:[0,1,1]
	v_pk_fma_f32 v[36:37], v[112:113], v[150:151], v[36:37] op_sel_hi:[0,1,1]
	v_pk_fma_f32 v[38:39], v[112:113], v[152:153], v[38:39] op_sel_hi:[0,1,1]
	v_pk_fma_f32 v[40:41], v[112:113], v[154:155], v[40:41] op_sel_hi:[0,1,1]
	v_pk_fma_f32 v[42:43], v[112:113], v[156:157], v[42:43] op_sel_hi:[0,1,1]
	v_pk_fma_f32 v[20:21], v[112:113], v[158:159], v[20:21] op_sel_hi:[0,1,1]
	s_waitcnt lgkmcnt(0)
	ds_read_b128 v[128:131], v11 offset:2336
	ds_read_b128 v[132:135], v11 offset:2352
	ds_read_b128 v[136:139], v11 offset:2304
	ds_read_b128 v[140:143], v11 offset:2320
	ds_read_b128 v[144:147], v11 offset:2400
	ds_read_b128 v[148:151], v11 offset:2416
	ds_read_b128 v[152:155], v11 offset:2368
	ds_read_b128 v[156:159], v11 offset:2384
	v_pk_fma_f32 v[22:23], v[112:113], v[160:161], v[22:23] op_sel:[1,0,0] op_sel_hi:[1,1,1]
	v_pk_fma_f32 v[24:25], v[112:113], v[162:163], v[24:25] op_sel:[1,0,0] op_sel_hi:[1,1,1]
	v_pk_fma_f32 v[26:27], v[112:113], v[164:165], v[26:27] op_sel:[1,0,0] op_sel_hi:[1,1,1]
	v_pk_fma_f32 v[30:31], v[112:113], v[166:167], v[30:31] op_sel:[1,0,0] op_sel_hi:[1,1,1]
	v_pk_fma_f32 v[44:45], v[112:113], v[168:169], v[44:45] op_sel:[1,0,0] op_sel_hi:[1,1,1]
	v_pk_fma_f32 v[46:47], v[112:113], v[170:171], v[46:47] op_sel:[1,0,0] op_sel_hi:[1,1,1]
	v_pk_fma_f32 v[48:49], v[112:113], v[172:173], v[48:49] op_sel:[1,0,0] op_sel_hi:[1,1,1]
	v_pk_fma_f32 v[50:51], v[112:113], v[174:175], v[50:51] op_sel:[1,0,0] op_sel_hi:[1,1,1]
	v_pk_fma_f32 v[28:29], v[112:113], v[176:177], v[28:29] op_sel:[1,0,0] op_sel_hi:[1,1,1]
	v_pk_fma_f32 v[32:33], v[112:113], v[178:179], v[32:33] op_sel:[1,0,0] op_sel_hi:[1,1,1]
	v_pk_fma_f32 v[34:35], v[112:113], v[180:181], v[34:35] op_sel:[1,0,0] op_sel_hi:[1,1,1]
	v_pk_fma_f32 v[36:37], v[112:113], v[182:183], v[36:37] op_sel:[1,0,0] op_sel_hi:[1,1,1]
	v_pk_fma_f32 v[38:39], v[112:113], v[184:185], v[38:39] op_sel:[1,0,0] op_sel_hi:[1,1,1]
	v_pk_fma_f32 v[40:41], v[112:113], v[186:187], v[40:41] op_sel:[1,0,0] op_sel_hi:[1,1,1]
	v_pk_fma_f32 v[42:43], v[112:113], v[188:189], v[42:43] op_sel:[1,0,0] op_sel_hi:[1,1,1]
	v_pk_fma_f32 v[20:21], v[112:113], v[190:191], v[20:21] op_sel:[1,0,0] op_sel_hi:[1,1,1]
	s_waitcnt lgkmcnt(0)
	ds_read_b128 v[160:163], v11 offset:2480
	ds_read_b128 v[164:167], v11 offset:2464
	ds_read_b128 v[168:171], v11 offset:2448
	ds_read_b128 v[172:175], v11 offset:2432
	ds_read_b128 v[176:179], v11 offset:2544
	ds_read_b128 v[180:183], v11 offset:2528
	ds_read_b128 v[184:187], v11 offset:2512
	ds_read_b128 v[188:191], v11 offset:2496
	v_pk_fma_f32 v[22:23], v[114:115], v[128:129], v[22:23] op_sel_hi:[0,1,1]
	v_pk_fma_f32 v[24:25], v[114:115], v[130:131], v[24:25] op_sel_hi:[0,1,1]
	v_pk_fma_f32 v[26:27], v[114:115], v[132:133], v[26:27] op_sel_hi:[0,1,1]
	v_pk_fma_f32 v[30:31], v[114:115], v[134:135], v[30:31] op_sel_hi:[0,1,1]
	v_pk_fma_f32 v[44:45], v[114:115], v[136:137], v[44:45] op_sel_hi:[0,1,1]
	v_pk_fma_f32 v[46:47], v[114:115], v[138:139], v[46:47] op_sel_hi:[0,1,1]
	v_pk_fma_f32 v[48:49], v[114:115], v[140:141], v[48:49] op_sel_hi:[0,1,1]
	v_pk_fma_f32 v[50:51], v[114:115], v[142:143], v[50:51] op_sel_hi:[0,1,1]
	v_pk_fma_f32 v[28:29], v[114:115], v[144:145], v[28:29] op_sel_hi:[0,1,1]
	v_pk_fma_f32 v[32:33], v[114:115], v[146:147], v[32:33] op_sel_hi:[0,1,1]
	v_pk_fma_f32 v[34:35], v[114:115], v[148:149], v[34:35] op_sel_hi:[0,1,1]
	v_pk_fma_f32 v[36:37], v[114:115], v[150:151], v[36:37] op_sel_hi:[0,1,1]
	v_pk_fma_f32 v[38:39], v[114:115], v[152:153], v[38:39] op_sel_hi:[0,1,1]
	v_pk_fma_f32 v[40:41], v[114:115], v[154:155], v[40:41] op_sel_hi:[0,1,1]
	v_pk_fma_f32 v[42:43], v[114:115], v[156:157], v[42:43] op_sel_hi:[0,1,1]
	v_pk_fma_f32 v[20:21], v[114:115], v[158:159], v[20:21] op_sel_hi:[0,1,1]
	s_waitcnt lgkmcnt(0)
	ds_read_b128 v[128:131], v11 offset:2624
	ds_read_b128 v[132:135], v11 offset:2640
	ds_read_b128 v[136:139], v11 offset:2656
	ds_read_b128 v[140:143], v11 offset:2672
	ds_read_b128 v[144:147], v11 offset:2560
	ds_read_b128 v[148:151], v11 offset:2576
	ds_read_b128 v[152:155], v11 offset:2592
	ds_read_b128 v[156:159], v11 offset:2608
	v_pk_fma_f32 v[22:23], v[114:115], v[160:161], v[22:23] op_sel:[1,0,0] op_sel_hi:[1,1,1]
	v_pk_fma_f32 v[24:25], v[114:115], v[162:163], v[24:25] op_sel:[1,0,0] op_sel_hi:[1,1,1]
	v_pk_fma_f32 v[26:27], v[114:115], v[164:165], v[26:27] op_sel:[1,0,0] op_sel_hi:[1,1,1]
	v_pk_fma_f32 v[30:31], v[114:115], v[166:167], v[30:31] op_sel:[1,0,0] op_sel_hi:[1,1,1]
	v_pk_fma_f32 v[44:45], v[114:115], v[168:169], v[44:45] op_sel:[1,0,0] op_sel_hi:[1,1,1]
	v_pk_fma_f32 v[46:47], v[114:115], v[170:171], v[46:47] op_sel:[1,0,0] op_sel_hi:[1,1,1]
	v_pk_fma_f32 v[48:49], v[114:115], v[172:173], v[48:49] op_sel:[1,0,0] op_sel_hi:[1,1,1]
	v_pk_fma_f32 v[50:51], v[114:115], v[174:175], v[50:51] op_sel:[1,0,0] op_sel_hi:[1,1,1]
	v_pk_fma_f32 v[28:29], v[114:115], v[176:177], v[28:29] op_sel:[1,0,0] op_sel_hi:[1,1,1]
	v_pk_fma_f32 v[32:33], v[114:115], v[178:179], v[32:33] op_sel:[1,0,0] op_sel_hi:[1,1,1]
	v_pk_fma_f32 v[34:35], v[114:115], v[180:181], v[34:35] op_sel:[1,0,0] op_sel_hi:[1,1,1]
	v_pk_fma_f32 v[36:37], v[114:115], v[182:183], v[36:37] op_sel:[1,0,0] op_sel_hi:[1,1,1]
	v_pk_fma_f32 v[38:39], v[114:115], v[184:185], v[38:39] op_sel:[1,0,0] op_sel_hi:[1,1,1]
	v_pk_fma_f32 v[40:41], v[114:115], v[186:187], v[40:41] op_sel:[1,0,0] op_sel_hi:[1,1,1]
	v_pk_fma_f32 v[42:43], v[114:115], v[188:189], v[42:43] op_sel:[1,0,0] op_sel_hi:[1,1,1]
	v_pk_fma_f32 v[20:21], v[114:115], v[190:191], v[20:21] op_sel:[1,0,0] op_sel_hi:[1,1,1]
	s_waitcnt lgkmcnt(0)
	ds_read_b128 v[160:163], v11 offset:2768
	ds_read_b128 v[164:167], v11 offset:2752
	ds_read_b128 v[168:171], v11 offset:2800
	ds_read_b128 v[172:175], v11 offset:2784
	ds_read_b128 v[176:179], v11 offset:2704
	ds_read_b128 v[180:183], v11 offset:2688
	ds_read_b128 v[184:187], v11 offset:2736
	ds_read_b128 v[188:191], v11 offset:2720
	v_pk_fma_f32 v[22:23], v[116:117], v[128:129], v[22:23] op_sel_hi:[0,1,1]
	v_pk_fma_f32 v[24:25], v[116:117], v[130:131], v[24:25] op_sel_hi:[0,1,1]
	v_pk_fma_f32 v[26:27], v[116:117], v[132:133], v[26:27] op_sel_hi:[0,1,1]
	v_pk_fma_f32 v[30:31], v[116:117], v[134:135], v[30:31] op_sel_hi:[0,1,1]
	v_pk_fma_f32 v[44:45], v[116:117], v[136:137], v[44:45] op_sel_hi:[0,1,1]
	v_pk_fma_f32 v[46:47], v[116:117], v[138:139], v[46:47] op_sel_hi:[0,1,1]
	v_pk_fma_f32 v[48:49], v[116:117], v[140:141], v[48:49] op_sel_hi:[0,1,1]
	v_pk_fma_f32 v[50:51], v[116:117], v[142:143], v[50:51] op_sel_hi:[0,1,1]
	v_pk_fma_f32 v[28:29], v[116:117], v[144:145], v[28:29] op_sel_hi:[0,1,1]
	v_pk_fma_f32 v[32:33], v[116:117], v[146:147], v[32:33] op_sel_hi:[0,1,1]
	v_pk_fma_f32 v[34:35], v[116:117], v[148:149], v[34:35] op_sel_hi:[0,1,1]
	v_pk_fma_f32 v[36:37], v[116:117], v[150:151], v[36:37] op_sel_hi:[0,1,1]
	v_pk_fma_f32 v[38:39], v[116:117], v[152:153], v[38:39] op_sel_hi:[0,1,1]
	v_pk_fma_f32 v[40:41], v[116:117], v[154:155], v[40:41] op_sel_hi:[0,1,1]
	v_pk_fma_f32 v[42:43], v[116:117], v[156:157], v[42:43] op_sel_hi:[0,1,1]
	v_pk_fma_f32 v[20:21], v[116:117], v[158:159], v[20:21] op_sel_hi:[0,1,1]
	s_waitcnt lgkmcnt(0)
	ds_read_b128 v[128:131], v11 offset:2912
	ds_read_b128 v[132:135], v11 offset:2928
	ds_read_b128 v[136:139], v11 offset:2880
	ds_read_b128 v[140:143], v11 offset:2896
	ds_read_b128 v[144:147], v11 offset:2848
	ds_read_b128 v[148:151], v11 offset:2864
	ds_read_b128 v[152:155], v11 offset:2816
	ds_read_b128 v[156:159], v11 offset:2832
	v_pk_fma_f32 v[22:23], v[116:117], v[160:161], v[22:23] op_sel:[1,0,0] op_sel_hi:[1,1,1]
	v_pk_fma_f32 v[24:25], v[116:117], v[162:163], v[24:25] op_sel:[1,0,0] op_sel_hi:[1,1,1]
	v_pk_fma_f32 v[26:27], v[116:117], v[164:165], v[26:27] op_sel:[1,0,0] op_sel_hi:[1,1,1]
	v_pk_fma_f32 v[30:31], v[116:117], v[166:167], v[30:31] op_sel:[1,0,0] op_sel_hi:[1,1,1]
	v_pk_fma_f32 v[44:45], v[116:117], v[168:169], v[44:45] op_sel:[1,0,0] op_sel_hi:[1,1,1]
	v_pk_fma_f32 v[46:47], v[116:117], v[170:171], v[46:47] op_sel:[1,0,0] op_sel_hi:[1,1,1]
	v_pk_fma_f32 v[48:49], v[116:117], v[172:173], v[48:49] op_sel:[1,0,0] op_sel_hi:[1,1,1]
	v_pk_fma_f32 v[50:51], v[116:117], v[174:175], v[50:51] op_sel:[1,0,0] op_sel_hi:[1,1,1]
	v_pk_fma_f32 v[28:29], v[116:117], v[176:177], v[28:29] op_sel:[1,0,0] op_sel_hi:[1,1,1]
	v_pk_fma_f32 v[32:33], v[116:117], v[178:179], v[32:33] op_sel:[1,0,0] op_sel_hi:[1,1,1]
	v_pk_fma_f32 v[34:35], v[116:117], v[180:181], v[34:35] op_sel:[1,0,0] op_sel_hi:[1,1,1]
	v_pk_fma_f32 v[36:37], v[116:117], v[182:183], v[36:37] op_sel:[1,0,0] op_sel_hi:[1,1,1]
	v_pk_fma_f32 v[38:39], v[116:117], v[184:185], v[38:39] op_sel:[1,0,0] op_sel_hi:[1,1,1]
	v_pk_fma_f32 v[40:41], v[116:117], v[186:187], v[40:41] op_sel:[1,0,0] op_sel_hi:[1,1,1]
	v_pk_fma_f32 v[42:43], v[116:117], v[188:189], v[42:43] op_sel:[1,0,0] op_sel_hi:[1,1,1]
	v_pk_fma_f32 v[20:21], v[116:117], v[190:191], v[20:21] op_sel:[1,0,0] op_sel_hi:[1,1,1]
	s_waitcnt lgkmcnt(0)
	ds_read_b128 v[160:163], v11 offset:3056
	ds_read_b128 v[164:167], v11 offset:3040
	ds_read_b128 v[168:171], v11 offset:3024
	ds_read_b128 v[172:175], v11 offset:3008
	ds_read_b128 v[176:179], v11 offset:2992
	ds_read_b128 v[180:183], v11 offset:2976
	ds_read_b128 v[184:187], v11 offset:2960
	ds_read_b128 v[188:191], v11 offset:2944
	v_pk_fma_f32 v[22:23], v[118:119], v[128:129], v[22:23] op_sel_hi:[0,1,1]
	v_pk_fma_f32 v[24:25], v[118:119], v[130:131], v[24:25] op_sel_hi:[0,1,1]
	v_pk_fma_f32 v[26:27], v[118:119], v[132:133], v[26:27] op_sel_hi:[0,1,1]
	v_pk_fma_f32 v[30:31], v[118:119], v[134:135], v[30:31] op_sel_hi:[0,1,1]
	v_pk_fma_f32 v[44:45], v[118:119], v[136:137], v[44:45] op_sel_hi:[0,1,1]
	v_pk_fma_f32 v[46:47], v[118:119], v[138:139], v[46:47] op_sel_hi:[0,1,1]
	v_pk_fma_f32 v[48:49], v[118:119], v[140:141], v[48:49] op_sel_hi:[0,1,1]
	v_pk_fma_f32 v[50:51], v[118:119], v[142:143], v[50:51] op_sel_hi:[0,1,1]
	v_pk_fma_f32 v[28:29], v[118:119], v[144:145], v[28:29] op_sel_hi:[0,1,1]
	v_pk_fma_f32 v[32:33], v[118:119], v[146:147], v[32:33] op_sel_hi:[0,1,1]
	v_pk_fma_f32 v[34:35], v[118:119], v[148:149], v[34:35] op_sel_hi:[0,1,1]
	v_pk_fma_f32 v[36:37], v[118:119], v[150:151], v[36:37] op_sel_hi:[0,1,1]
	v_pk_fma_f32 v[38:39], v[118:119], v[152:153], v[38:39] op_sel_hi:[0,1,1]
	v_pk_fma_f32 v[40:41], v[118:119], v[154:155], v[40:41] op_sel_hi:[0,1,1]
	v_pk_fma_f32 v[42:43], v[118:119], v[156:157], v[42:43] op_sel_hi:[0,1,1]
	v_pk_fma_f32 v[20:21], v[118:119], v[158:159], v[20:21] op_sel_hi:[0,1,1]
	s_waitcnt lgkmcnt(0)
	ds_read_b128 v[128:131], v11 offset:3072
	ds_read_b128 v[132:135], v11 offset:3088
	ds_read_b128 v[136:139], v11 offset:3104
	ds_read_b128 v[140:143], v11 offset:3120
	ds_read_b128 v[144:147], v11 offset:3136
	ds_read_b128 v[148:151], v11 offset:3152
	ds_read_b128 v[152:155], v11 offset:3168
	ds_read_b128 v[156:159], v11 offset:3184
	v_pk_fma_f32 v[22:23], v[118:119], v[160:161], v[22:23] op_sel:[1,0,0] op_sel_hi:[1,1,1]
	v_pk_fma_f32 v[24:25], v[118:119], v[162:163], v[24:25] op_sel:[1,0,0] op_sel_hi:[1,1,1]
	v_pk_fma_f32 v[26:27], v[118:119], v[164:165], v[26:27] op_sel:[1,0,0] op_sel_hi:[1,1,1]
	v_pk_fma_f32 v[30:31], v[118:119], v[166:167], v[30:31] op_sel:[1,0,0] op_sel_hi:[1,1,1]
	v_pk_fma_f32 v[44:45], v[118:119], v[168:169], v[44:45] op_sel:[1,0,0] op_sel_hi:[1,1,1]
	v_pk_fma_f32 v[46:47], v[118:119], v[170:171], v[46:47] op_sel:[1,0,0] op_sel_hi:[1,1,1]
	v_pk_fma_f32 v[48:49], v[118:119], v[172:173], v[48:49] op_sel:[1,0,0] op_sel_hi:[1,1,1]
	v_pk_fma_f32 v[50:51], v[118:119], v[174:175], v[50:51] op_sel:[1,0,0] op_sel_hi:[1,1,1]
	v_pk_fma_f32 v[28:29], v[118:119], v[176:177], v[28:29] op_sel:[1,0,0] op_sel_hi:[1,1,1]
	v_pk_fma_f32 v[32:33], v[118:119], v[178:179], v[32:33] op_sel:[1,0,0] op_sel_hi:[1,1,1]
	v_pk_fma_f32 v[34:35], v[118:119], v[180:181], v[34:35] op_sel:[1,0,0] op_sel_hi:[1,1,1]
	v_pk_fma_f32 v[36:37], v[118:119], v[182:183], v[36:37] op_sel:[1,0,0] op_sel_hi:[1,1,1]
	v_pk_fma_f32 v[38:39], v[118:119], v[184:185], v[38:39] op_sel:[1,0,0] op_sel_hi:[1,1,1]
	v_pk_fma_f32 v[40:41], v[118:119], v[186:187], v[40:41] op_sel:[1,0,0] op_sel_hi:[1,1,1]
	v_pk_fma_f32 v[42:43], v[118:119], v[188:189], v[42:43] op_sel:[1,0,0] op_sel_hi:[1,1,1]
	v_pk_fma_f32 v[20:21], v[118:119], v[190:191], v[20:21] op_sel:[1,0,0] op_sel_hi:[1,1,1]
	s_waitcnt lgkmcnt(0)
	ds_read_b128 v[160:163], v11 offset:3216
	ds_read_b128 v[164:167], v11 offset:3200
	ds_read_b128 v[168:171], v11 offset:3248
	ds_read_b128 v[172:175], v11 offset:3232
	ds_read_b128 v[176:179], v11 offset:3280
	ds_read_b128 v[180:183], v11 offset:3264
	ds_read_b128 v[184:187], v11 offset:3312
	ds_read_b128 v[188:191], v11 offset:3296
	v_pk_fma_f32 v[22:23], v[120:121], v[128:129], v[22:23] op_sel_hi:[0,1,1]
	v_pk_fma_f32 v[24:25], v[120:121], v[130:131], v[24:25] op_sel_hi:[0,1,1]
	v_pk_fma_f32 v[26:27], v[120:121], v[132:133], v[26:27] op_sel_hi:[0,1,1]
	v_pk_fma_f32 v[30:31], v[120:121], v[134:135], v[30:31] op_sel_hi:[0,1,1]
	v_pk_fma_f32 v[44:45], v[120:121], v[136:137], v[44:45] op_sel_hi:[0,1,1]
	v_pk_fma_f32 v[46:47], v[120:121], v[138:139], v[46:47] op_sel_hi:[0,1,1]
	v_pk_fma_f32 v[48:49], v[120:121], v[140:141], v[48:49] op_sel_hi:[0,1,1]
	v_pk_fma_f32 v[50:51], v[120:121], v[142:143], v[50:51] op_sel_hi:[0,1,1]
	v_pk_fma_f32 v[28:29], v[120:121], v[144:145], v[28:29] op_sel_hi:[0,1,1]
	v_pk_fma_f32 v[32:33], v[120:121], v[146:147], v[32:33] op_sel_hi:[0,1,1]
	v_pk_fma_f32 v[34:35], v[120:121], v[148:149], v[34:35] op_sel_hi:[0,1,1]
	v_pk_fma_f32 v[36:37], v[120:121], v[150:151], v[36:37] op_sel_hi:[0,1,1]
	v_pk_fma_f32 v[38:39], v[120:121], v[152:153], v[38:39] op_sel_hi:[0,1,1]
	v_pk_fma_f32 v[40:41], v[120:121], v[154:155], v[40:41] op_sel_hi:[0,1,1]
	v_pk_fma_f32 v[42:43], v[120:121], v[156:157], v[42:43] op_sel_hi:[0,1,1]
	v_pk_fma_f32 v[20:21], v[120:121], v[158:159], v[20:21] op_sel_hi:[0,1,1]
	s_waitcnt lgkmcnt(0)
	ds_read_b128 v[128:131], v11 offset:3360
	ds_read_b128 v[132:135], v11 offset:3376
	ds_read_b128 v[136:139], v11 offset:3328
	ds_read_b128 v[140:143], v11 offset:3344
	ds_read_b128 v[144:147], v11 offset:3424
	ds_read_b128 v[148:151], v11 offset:3440
	ds_read_b128 v[152:155], v11 offset:3392
	ds_read_b128 v[156:159], v11 offset:3408
	v_pk_fma_f32 v[22:23], v[120:121], v[160:161], v[22:23] op_sel:[1,0,0] op_sel_hi:[1,1,1]
	v_pk_fma_f32 v[24:25], v[120:121], v[162:163], v[24:25] op_sel:[1,0,0] op_sel_hi:[1,1,1]
	v_pk_fma_f32 v[26:27], v[120:121], v[164:165], v[26:27] op_sel:[1,0,0] op_sel_hi:[1,1,1]
	v_pk_fma_f32 v[30:31], v[120:121], v[166:167], v[30:31] op_sel:[1,0,0] op_sel_hi:[1,1,1]
	v_pk_fma_f32 v[44:45], v[120:121], v[168:169], v[44:45] op_sel:[1,0,0] op_sel_hi:[1,1,1]
	v_pk_fma_f32 v[46:47], v[120:121], v[170:171], v[46:47] op_sel:[1,0,0] op_sel_hi:[1,1,1]
	v_pk_fma_f32 v[48:49], v[120:121], v[172:173], v[48:49] op_sel:[1,0,0] op_sel_hi:[1,1,1]
	v_pk_fma_f32 v[50:51], v[120:121], v[174:175], v[50:51] op_sel:[1,0,0] op_sel_hi:[1,1,1]
	v_pk_fma_f32 v[28:29], v[120:121], v[176:177], v[28:29] op_sel:[1,0,0] op_sel_hi:[1,1,1]
	v_pk_fma_f32 v[32:33], v[120:121], v[178:179], v[32:33] op_sel:[1,0,0] op_sel_hi:[1,1,1]
	v_pk_fma_f32 v[34:35], v[120:121], v[180:181], v[34:35] op_sel:[1,0,0] op_sel_hi:[1,1,1]
	v_pk_fma_f32 v[36:37], v[120:121], v[182:183], v[36:37] op_sel:[1,0,0] op_sel_hi:[1,1,1]
	v_pk_fma_f32 v[38:39], v[120:121], v[184:185], v[38:39] op_sel:[1,0,0] op_sel_hi:[1,1,1]
	v_pk_fma_f32 v[40:41], v[120:121], v[186:187], v[40:41] op_sel:[1,0,0] op_sel_hi:[1,1,1]
	v_pk_fma_f32 v[42:43], v[120:121], v[188:189], v[42:43] op_sel:[1,0,0] op_sel_hi:[1,1,1]
	v_pk_fma_f32 v[20:21], v[120:121], v[190:191], v[20:21] op_sel:[1,0,0] op_sel_hi:[1,1,1]
	s_waitcnt lgkmcnt(0)
	ds_read_b128 v[160:163], v11 offset:3504
	ds_read_b128 v[164:167], v11 offset:3488
	ds_read_b128 v[168:171], v11 offset:3472
	ds_read_b128 v[172:175], v11 offset:3456
	ds_read_b128 v[176:179], v11 offset:3568
	ds_read_b128 v[180:183], v11 offset:3552
	ds_read_b128 v[184:187], v11 offset:3536
	ds_read_b128 v[188:191], v11 offset:3520
	v_pk_fma_f32 v[22:23], v[122:123], v[128:129], v[22:23] op_sel_hi:[0,1,1]
	v_pk_fma_f32 v[24:25], v[122:123], v[130:131], v[24:25] op_sel_hi:[0,1,1]
	v_pk_fma_f32 v[26:27], v[122:123], v[132:133], v[26:27] op_sel_hi:[0,1,1]
	v_pk_fma_f32 v[30:31], v[122:123], v[134:135], v[30:31] op_sel_hi:[0,1,1]
	v_pk_fma_f32 v[44:45], v[122:123], v[136:137], v[44:45] op_sel_hi:[0,1,1]
	v_pk_fma_f32 v[46:47], v[122:123], v[138:139], v[46:47] op_sel_hi:[0,1,1]
	v_pk_fma_f32 v[48:49], v[122:123], v[140:141], v[48:49] op_sel_hi:[0,1,1]
	v_pk_fma_f32 v[50:51], v[122:123], v[142:143], v[50:51] op_sel_hi:[0,1,1]
	v_pk_fma_f32 v[28:29], v[122:123], v[144:145], v[28:29] op_sel_hi:[0,1,1]
	v_pk_fma_f32 v[32:33], v[122:123], v[146:147], v[32:33] op_sel_hi:[0,1,1]
	v_pk_fma_f32 v[34:35], v[122:123], v[148:149], v[34:35] op_sel_hi:[0,1,1]
	v_pk_fma_f32 v[36:37], v[122:123], v[150:151], v[36:37] op_sel_hi:[0,1,1]
	v_pk_fma_f32 v[38:39], v[122:123], v[152:153], v[38:39] op_sel_hi:[0,1,1]
	v_pk_fma_f32 v[40:41], v[122:123], v[154:155], v[40:41] op_sel_hi:[0,1,1]
	v_pk_fma_f32 v[42:43], v[122:123], v[156:157], v[42:43] op_sel_hi:[0,1,1]
	v_pk_fma_f32 v[20:21], v[122:123], v[158:159], v[20:21] op_sel_hi:[0,1,1]
	s_waitcnt lgkmcnt(0)
	ds_read_b128 v[128:131], v11 offset:3648
	ds_read_b128 v[132:135], v11 offset:3664
	ds_read_b128 v[136:139], v11 offset:3680
	ds_read_b128 v[140:143], v11 offset:3696
	ds_read_b128 v[144:147], v11 offset:3584
	ds_read_b128 v[148:151], v11 offset:3600
	ds_read_b128 v[152:155], v11 offset:3616
	ds_read_b128 v[156:159], v11 offset:3632
	v_pk_fma_f32 v[22:23], v[122:123], v[160:161], v[22:23] op_sel:[1,0,0] op_sel_hi:[1,1,1]
	v_pk_fma_f32 v[24:25], v[122:123], v[162:163], v[24:25] op_sel:[1,0,0] op_sel_hi:[1,1,1]
	v_pk_fma_f32 v[26:27], v[122:123], v[164:165], v[26:27] op_sel:[1,0,0] op_sel_hi:[1,1,1]
	v_pk_fma_f32 v[30:31], v[122:123], v[166:167], v[30:31] op_sel:[1,0,0] op_sel_hi:[1,1,1]
	v_pk_fma_f32 v[44:45], v[122:123], v[168:169], v[44:45] op_sel:[1,0,0] op_sel_hi:[1,1,1]
	v_pk_fma_f32 v[46:47], v[122:123], v[170:171], v[46:47] op_sel:[1,0,0] op_sel_hi:[1,1,1]
	v_pk_fma_f32 v[48:49], v[122:123], v[172:173], v[48:49] op_sel:[1,0,0] op_sel_hi:[1,1,1]
	v_pk_fma_f32 v[50:51], v[122:123], v[174:175], v[50:51] op_sel:[1,0,0] op_sel_hi:[1,1,1]
	v_pk_fma_f32 v[28:29], v[122:123], v[176:177], v[28:29] op_sel:[1,0,0] op_sel_hi:[1,1,1]
	v_pk_fma_f32 v[32:33], v[122:123], v[178:179], v[32:33] op_sel:[1,0,0] op_sel_hi:[1,1,1]
	v_pk_fma_f32 v[34:35], v[122:123], v[180:181], v[34:35] op_sel:[1,0,0] op_sel_hi:[1,1,1]
	v_pk_fma_f32 v[36:37], v[122:123], v[182:183], v[36:37] op_sel:[1,0,0] op_sel_hi:[1,1,1]
	v_pk_fma_f32 v[38:39], v[122:123], v[184:185], v[38:39] op_sel:[1,0,0] op_sel_hi:[1,1,1]
	v_pk_fma_f32 v[40:41], v[122:123], v[186:187], v[40:41] op_sel:[1,0,0] op_sel_hi:[1,1,1]
	v_pk_fma_f32 v[42:43], v[122:123], v[188:189], v[42:43] op_sel:[1,0,0] op_sel_hi:[1,1,1]
	v_pk_fma_f32 v[20:21], v[122:123], v[190:191], v[20:21] op_sel:[1,0,0] op_sel_hi:[1,1,1]
	s_waitcnt lgkmcnt(0)
	ds_read_b128 v[160:163], v11 offset:3792
	ds_read_b128 v[164:167], v11 offset:3776
	ds_read_b128 v[168:171], v11 offset:3824
	ds_read_b128 v[172:175], v11 offset:3808
	ds_read_b128 v[176:179], v11 offset:3728
	ds_read_b128 v[180:183], v11 offset:3712
	ds_read_b128 v[184:187], v11 offset:3760
	ds_read_b128 v[188:191], v11 offset:3744
	v_pk_fma_f32 v[22:23], v[124:125], v[128:129], v[22:23] op_sel_hi:[0,1,1]
	v_pk_fma_f32 v[24:25], v[124:125], v[130:131], v[24:25] op_sel_hi:[0,1,1]
	v_pk_fma_f32 v[26:27], v[124:125], v[132:133], v[26:27] op_sel_hi:[0,1,1]
	v_pk_fma_f32 v[30:31], v[124:125], v[134:135], v[30:31] op_sel_hi:[0,1,1]
	v_pk_fma_f32 v[44:45], v[124:125], v[136:137], v[44:45] op_sel_hi:[0,1,1]
	v_pk_fma_f32 v[46:47], v[124:125], v[138:139], v[46:47] op_sel_hi:[0,1,1]
	v_pk_fma_f32 v[48:49], v[124:125], v[140:141], v[48:49] op_sel_hi:[0,1,1]
	v_pk_fma_f32 v[50:51], v[124:125], v[142:143], v[50:51] op_sel_hi:[0,1,1]
	v_pk_fma_f32 v[28:29], v[124:125], v[144:145], v[28:29] op_sel_hi:[0,1,1]
	v_pk_fma_f32 v[32:33], v[124:125], v[146:147], v[32:33] op_sel_hi:[0,1,1]
	v_pk_fma_f32 v[34:35], v[124:125], v[148:149], v[34:35] op_sel_hi:[0,1,1]
	v_pk_fma_f32 v[36:37], v[124:125], v[150:151], v[36:37] op_sel_hi:[0,1,1]
	v_pk_fma_f32 v[38:39], v[124:125], v[152:153], v[38:39] op_sel_hi:[0,1,1]
	v_pk_fma_f32 v[40:41], v[124:125], v[154:155], v[40:41] op_sel_hi:[0,1,1]
	v_pk_fma_f32 v[42:43], v[124:125], v[156:157], v[42:43] op_sel_hi:[0,1,1]
	v_pk_fma_f32 v[20:21], v[124:125], v[158:159], v[20:21] op_sel_hi:[0,1,1]
	s_waitcnt lgkmcnt(0)
	ds_read_b128 v[128:131], v11 offset:3936
	ds_read_b128 v[132:135], v11 offset:3952
	ds_read_b128 v[136:139], v11 offset:3904
	ds_read_b128 v[140:143], v11 offset:3920
	ds_read_b128 v[144:147], v11 offset:3872
	ds_read_b128 v[148:151], v11 offset:3888
	ds_read_b128 v[152:155], v11 offset:3840
	ds_read_b128 v[156:159], v11 offset:3856
	v_pk_fma_f32 v[22:23], v[124:125], v[160:161], v[22:23] op_sel:[1,0,0] op_sel_hi:[1,1,1]
	v_pk_fma_f32 v[24:25], v[124:125], v[162:163], v[24:25] op_sel:[1,0,0] op_sel_hi:[1,1,1]
	v_pk_fma_f32 v[26:27], v[124:125], v[164:165], v[26:27] op_sel:[1,0,0] op_sel_hi:[1,1,1]
	v_pk_fma_f32 v[30:31], v[124:125], v[166:167], v[30:31] op_sel:[1,0,0] op_sel_hi:[1,1,1]
	v_pk_fma_f32 v[44:45], v[124:125], v[168:169], v[44:45] op_sel:[1,0,0] op_sel_hi:[1,1,1]
	v_pk_fma_f32 v[46:47], v[124:125], v[170:171], v[46:47] op_sel:[1,0,0] op_sel_hi:[1,1,1]
	v_pk_fma_f32 v[48:49], v[124:125], v[172:173], v[48:49] op_sel:[1,0,0] op_sel_hi:[1,1,1]
	v_pk_fma_f32 v[50:51], v[124:125], v[174:175], v[50:51] op_sel:[1,0,0] op_sel_hi:[1,1,1]
	v_pk_fma_f32 v[28:29], v[124:125], v[176:177], v[28:29] op_sel:[1,0,0] op_sel_hi:[1,1,1]
	v_pk_fma_f32 v[32:33], v[124:125], v[178:179], v[32:33] op_sel:[1,0,0] op_sel_hi:[1,1,1]
	v_pk_fma_f32 v[34:35], v[124:125], v[180:181], v[34:35] op_sel:[1,0,0] op_sel_hi:[1,1,1]
	v_pk_fma_f32 v[36:37], v[124:125], v[182:183], v[36:37] op_sel:[1,0,0] op_sel_hi:[1,1,1]
	v_pk_fma_f32 v[38:39], v[124:125], v[184:185], v[38:39] op_sel:[1,0,0] op_sel_hi:[1,1,1]
	v_pk_fma_f32 v[40:41], v[124:125], v[186:187], v[40:41] op_sel:[1,0,0] op_sel_hi:[1,1,1]
	v_pk_fma_f32 v[42:43], v[124:125], v[188:189], v[42:43] op_sel:[1,0,0] op_sel_hi:[1,1,1]
	v_pk_fma_f32 v[20:21], v[124:125], v[190:191], v[20:21] op_sel:[1,0,0] op_sel_hi:[1,1,1]
	s_waitcnt lgkmcnt(0)
	ds_read_b128 v[160:163], v11 offset:4080
	ds_read_b128 v[164:167], v11 offset:4064
	ds_read_b128 v[168:171], v11 offset:4048
	ds_read_b128 v[172:175], v11 offset:4032
	ds_read_b128 v[176:179], v11 offset:4016
	ds_read_b128 v[180:183], v11 offset:4000
	ds_read_b128 v[184:187], v11 offset:3984
	ds_read_b128 v[188:191], v11 offset:3968
	v_pk_fma_f32 v[22:23], v[126:127], v[128:129], v[22:23] op_sel_hi:[0,1,1]
	v_pk_fma_f32 v[24:25], v[126:127], v[130:131], v[24:25] op_sel_hi:[0,1,1]
	v_pk_fma_f32 v[26:27], v[126:127], v[132:133], v[26:27] op_sel_hi:[0,1,1]
	v_pk_fma_f32 v[30:31], v[126:127], v[134:135], v[30:31] op_sel_hi:[0,1,1]
	v_pk_fma_f32 v[44:45], v[126:127], v[136:137], v[44:45] op_sel_hi:[0,1,1]
	v_pk_fma_f32 v[46:47], v[126:127], v[138:139], v[46:47] op_sel_hi:[0,1,1]
	v_pk_fma_f32 v[48:49], v[126:127], v[140:141], v[48:49] op_sel_hi:[0,1,1]
	v_pk_fma_f32 v[50:51], v[126:127], v[142:143], v[50:51] op_sel_hi:[0,1,1]
	v_pk_fma_f32 v[28:29], v[126:127], v[144:145], v[28:29] op_sel_hi:[0,1,1]
	v_pk_fma_f32 v[32:33], v[126:127], v[146:147], v[32:33] op_sel_hi:[0,1,1]
	v_pk_fma_f32 v[34:35], v[126:127], v[148:149], v[34:35] op_sel_hi:[0,1,1]
	v_pk_fma_f32 v[36:37], v[126:127], v[150:151], v[36:37] op_sel_hi:[0,1,1]
	v_pk_fma_f32 v[38:39], v[126:127], v[152:153], v[38:39] op_sel_hi:[0,1,1]
	v_pk_fma_f32 v[40:41], v[126:127], v[154:155], v[40:41] op_sel_hi:[0,1,1]
	v_pk_fma_f32 v[42:43], v[126:127], v[156:157], v[42:43] op_sel_hi:[0,1,1]
	v_pk_fma_f32 v[20:21], v[126:127], v[158:159], v[20:21] op_sel_hi:[0,1,1]
	s_waitcnt lgkmcnt(0)
	v_pk_fma_f32 v[22:23], v[126:127], v[160:161], v[22:23] op_sel:[1,0,0] op_sel_hi:[1,1,1]
	v_pk_fma_f32 v[24:25], v[126:127], v[162:163], v[24:25] op_sel:[1,0,0] op_sel_hi:[1,1,1]
	v_pk_fma_f32 v[26:27], v[126:127], v[164:165], v[26:27] op_sel:[1,0,0] op_sel_hi:[1,1,1]
	v_pk_fma_f32 v[30:31], v[126:127], v[166:167], v[30:31] op_sel:[1,0,0] op_sel_hi:[1,1,1]
	v_pk_fma_f32 v[44:45], v[126:127], v[168:169], v[44:45] op_sel:[1,0,0] op_sel_hi:[1,1,1]
	v_pk_fma_f32 v[46:47], v[126:127], v[170:171], v[46:47] op_sel:[1,0,0] op_sel_hi:[1,1,1]
	v_pk_fma_f32 v[48:49], v[126:127], v[172:173], v[48:49] op_sel:[1,0,0] op_sel_hi:[1,1,1]
	v_pk_fma_f32 v[50:51], v[126:127], v[174:175], v[50:51] op_sel:[1,0,0] op_sel_hi:[1,1,1]
	v_pk_fma_f32 v[28:29], v[126:127], v[176:177], v[28:29] op_sel:[1,0,0] op_sel_hi:[1,1,1]
	v_pk_fma_f32 v[32:33], v[126:127], v[178:179], v[32:33] op_sel:[1,0,0] op_sel_hi:[1,1,1]
	v_pk_fma_f32 v[34:35], v[126:127], v[180:181], v[34:35] op_sel:[1,0,0] op_sel_hi:[1,1,1]
	v_pk_fma_f32 v[36:37], v[126:127], v[182:183], v[36:37] op_sel:[1,0,0] op_sel_hi:[1,1,1]
	v_pk_fma_f32 v[38:39], v[126:127], v[184:185], v[38:39] op_sel:[1,0,0] op_sel_hi:[1,1,1]
	v_pk_fma_f32 v[40:41], v[126:127], v[186:187], v[40:41] op_sel:[1,0,0] op_sel_hi:[1,1,1]
	v_pk_fma_f32 v[42:43], v[126:127], v[188:189], v[42:43] op_sel:[1,0,0] op_sel_hi:[1,1,1]
	v_pk_fma_f32 v[20:21], v[126:127], v[190:191], v[20:21] op_sel:[1,0,0] op_sel_hi:[1,1,1]
	s_lshl_b32 s0, s66, 6
	v_or_b32_e32 v16, s0, v199
	v_readlane_b32 s4, v249, 9
	v_ashrrev_i32_e32 v17, 31, v16
	v_readlane_b32 s10, v249, 15
	v_readlane_b32 s11, v249, 16
	s_barrier
	s_nop 0
	v_lshl_add_u64 v[16:17], v[16:17], 2, s[10:11]
	ds_write2st64_b32 v70, v22, v23 offset1:1
	ds_write2st64_b32 v70, v24, v25 offset0:2 offset1:3
	ds_write2st64_b32 v70, v26, v27 offset0:4 offset1:5
	ds_write2st64_b32 v70, v30, v31 offset0:6 offset1:7
	ds_write2st64_b32 v70, v44, v45 offset0:8 offset1:9
	ds_write2st64_b32 v70, v46, v47 offset0:10 offset1:11
	ds_write2st64_b32 v70, v48, v49 offset0:12 offset1:13
	ds_write2st64_b32 v70, v50, v51 offset0:14 offset1:15
	ds_write2st64_b32 v70, v28, v29 offset0:16 offset1:17
	ds_write2st64_b32 v70, v32, v33 offset0:18 offset1:19
	ds_write2st64_b32 v70, v34, v35 offset0:20 offset1:21
	ds_write2st64_b32 v70, v36, v37 offset0:22 offset1:23
	ds_write2st64_b32 v70, v38, v39 offset0:24 offset1:25
	ds_write2st64_b32 v70, v40, v41 offset0:26 offset1:27
	ds_write2st64_b32 v70, v42, v43 offset0:28 offset1:29
	ds_write2st64_b32 v70, v20, v21 offset0:30 offset1:31
	s_waitcnt lgkmcnt(0)
	s_barrier
	global_load_dword v11, v[16:17], off
	ds_read2st64_b32 v[18:19], v54 offset1:32
	ds_read2st64_b32 v[20:21], v54 offset0:64 offset1:96
	ds_read2st64_b32 v[22:23], v54 offset0:128 offset1:160
	ds_read2st64_b32 v[24:25], v54 offset0:192 offset1:224
	s_ashr_i32 s1, s0, 31
	v_lshl_add_u64 v[26:27], s[0:1], 2, v[4:5]
	v_lshl_add_u64 v[28:29], v[26:27], 0, v[2:3]
	v_mov_b32_e32 v15, v3
	s_add_i32 s66, s66, s82
	s_add_i32 s60, s60, s33
	s_cmpk_gt_i32 s66, 0x5f
	v_readlane_b32 s5, v249, 10
	v_readlane_b32 s6, v249, 11
	v_readlane_b32 s7, v249, 12
	v_readlane_b32 s8, v249, 13
	v_readlane_b32 s9, v249, 14
	v_readlane_b32 s12, v249, 17
	v_readlane_b32 s13, v249, 18
	v_readlane_b32 s14, v249, 19
	v_readlane_b32 s15, v249, 20
	v_readlane_b32 s16, v249, 21
	v_readlane_b32 s17, v249, 22
	v_readlane_b32 s18, v249, 23
	v_readlane_b32 s19, v249, 24
	s_waitcnt vmcnt(0) lgkmcnt(3)
	v_add_f32_e32 v11, v11, v18
	v_add_f32_e32 v11, v11, v19
	s_waitcnt lgkmcnt(2)
	v_add_f32_e32 v11, v11, v20
	v_add_f32_e32 v11, v11, v21
	s_waitcnt lgkmcnt(1)
	v_add_f32_e32 v11, v11, v22
	v_add_f32_e32 v11, v11, v23
	s_waitcnt lgkmcnt(0)
	v_add_f32_e32 v11, v11, v24
	v_add_f32_e32 v11, v11, v25
	global_store_dword v[28:29], v11, off
	global_load_dword v13, v[16:17], off
	ds_read2st64_b32 v[18:19], v55 offset1:32
	ds_read2st64_b32 v[20:21], v55 offset0:64 offset1:96
	ds_read2st64_b32 v[22:23], v55 offset0:128 offset1:160
	ds_read2st64_b32 v[24:25], v55 offset0:192 offset1:224
	v_mov_b32_e32 v11, v3
	v_lshl_add_u64 v[28:29], v[26:27], 0, v[10:11]
	s_waitcnt vmcnt(0) lgkmcnt(3)
	v_add_f32_e32 v11, v13, v18
	v_add_f32_e32 v11, v11, v19
	s_waitcnt lgkmcnt(2)
	v_add_f32_e32 v11, v11, v20
	v_add_f32_e32 v11, v11, v21
	s_waitcnt lgkmcnt(1)
	v_add_f32_e32 v11, v11, v22
	v_add_f32_e32 v11, v11, v23
	s_waitcnt lgkmcnt(0)
	v_add_f32_e32 v11, v11, v24
	v_add_f32_e32 v11, v11, v25
	global_store_dword v[28:29], v11, off
	global_load_dword v11, v[16:17], off
	ds_read2st64_b32 v[18:19], v56 offset1:32
	ds_read2st64_b32 v[20:21], v56 offset0:64 offset1:96
	ds_read2st64_b32 v[22:23], v56 offset0:128 offset1:160
	ds_read2st64_b32 v[24:25], v56 offset0:192 offset1:224
	v_mov_b32_e32 v13, v3
	v_lshl_add_u64 v[28:29], v[26:27], 0, v[12:13]
	s_waitcnt vmcnt(0) lgkmcnt(3)
	v_add_f32_e32 v11, v11, v18
	v_add_f32_e32 v11, v11, v19
	s_waitcnt lgkmcnt(2)
	v_add_f32_e32 v11, v11, v20
	v_add_f32_e32 v11, v11, v21
	s_waitcnt lgkmcnt(1)
	v_add_f32_e32 v11, v11, v22
	v_add_f32_e32 v11, v11, v23
	s_waitcnt lgkmcnt(0)
	v_add_f32_e32 v11, v11, v24
	v_add_f32_e32 v11, v11, v25
	global_store_dword v[28:29], v11, off
	global_load_dword v11, v[16:17], off
	ds_read2st64_b32 v[16:17], v57 offset1:32
	ds_read2st64_b32 v[18:19], v57 offset0:64 offset1:96
	ds_read2st64_b32 v[20:21], v57 offset0:128 offset1:160
	ds_read2st64_b32 v[22:23], v57 offset0:192 offset1:224
	v_lshl_add_u64 v[24:25], v[26:27], 0, v[14:15]
	s_waitcnt vmcnt(0) lgkmcnt(3)
	v_add_f32_e32 v11, v11, v16
	v_add_f32_e32 v11, v11, v17
	s_waitcnt lgkmcnt(2)
	v_add_f32_e32 v11, v11, v18
	v_add_f32_e32 v11, v11, v19
	s_waitcnt lgkmcnt(1)
	v_add_f32_e32 v11, v11, v20
	v_add_f32_e32 v11, v11, v21
	s_waitcnt lgkmcnt(0)
	v_add_f32_e32 v11, v11, v22
	v_add_f32_e32 v11, v11, v23
	global_store_dword v[24:25], v11, off
	s_barrier
	s_cbranch_scc0 .LBB0_15
